# v124 extended: all 16 per-iteration LDS-DMA loads of every GEMM K-loop use the saddr form (m0 compensated for the +128 cases, old bases snapshotted in two SGPR pairs); no VALU address adds left in the
# speedup vs baseline: 1.0066x; 1.0016x over previous
; #define PG8_STAGE(bufoff, gbase, voff) do { _Pragma("unroll") for (int _i = 0; _i < 2; ++_i) \
;         __builtin_amdgcn_global_load_lds((const unsigned*)((const char*)(gbase) + (voff)[_i]), (PG8_LAS unsigned*)(lds + (bufoff) + ldsw + _i * 8192), 16, 0, 0); } while (0)
; #define PG8_LDA(dst, b, h) do { _Pragma("unroll") for (int m = 0; m < 4; ++m) _Pragma("unroll") for (int k = 0; k < 2; ++k) dst[m][k] = *(const PG8_LAS bf16x8*)(lds + PG8_SA(b, h) + aoff + m * 2048 + k * 1024); } while (0)
; #define PG8_LDB(dst, b, h) do { _Pragma("unroll") for (int n = 0; n < 2; ++n) _Pragma("unroll") for (int k = 0; k < 2; ++k) dst[n][k] = *(const PG8_LAS bf16x8*)(lds + PG8_SB(b, h) + boff + n * 2048 + k * 1024); } while (0)
; #define PG8_MMA(ai, bj, At, Bt) do { __builtin_amdgcn_s_setprio(1); _Pragma("unroll") for (int m = 0; m < 4; ++m) _Pragma("unroll") for (int n = 0; n < 2; ++n) _Pragma("unroll") for (int k = 0; k < 2; ++k) \
;         acc[ai][bj][m][n] = __builtin_amdgcn_mfma_f32_16x16x32_bf16(Bt[n][k], At[m][k], acc[ai][bj][m][n], 0, 0, 0); __builtin_amdgcn_s_setprio(0); } while (0)
; #define PG8_WAIT_V(n) asm volatile("s_waitcnt vmcnt(" #n ")" ::: "memory")
; #define PG8_WAIT_L(n) asm volatile("s_waitcnt lgkmcnt(" #n ")" ::: "memory")
; template <class Epi, class Sched, bool ALIGN_EPI = false, bool SP2 = false>
; __device__ __forceinline__ void gemm_phase(PG8_LAS unsigned char* lds, const Gemm g, const Sched& S, const Epi& E) {
;     ...
;             const bool last = (t == nt - 2);
;             const char* a1 = cA + (size_t)(t + 1) * kstep;
;             const char* a2 = last ? nA : cA + (size_t)(t + 2) * kstep; const char* b2 = last ? nB : cB + (size_t)(t + 2) * kstep;
;             const char* a3 = a2 + kstep; const char* b3 = b2 + kstep;
;             if (last && has_next) S.a_ready(nxt);
;             if constexpr (SP2) {
;             PG8_LDB(B0, 0, 0); PG8_LDB(B1, 0, 1); PG8_SCHED; PG8_LDA(At, 0, 0); PG8_STAGE(PG8_SA(1, 1), a1 + hstep, voffA);
;             PG8_WAIT_V(8); PG8_WAIT_L(0); PG8_BAR; PG8_MMA(0, 0, At, B0); PG8_MMA(0, 1, At, B1); PG8_BAR; PG8_SCHED;
;             PG8_LDA(At, 0, 1); PG8_STAGE(PG8_SB(0, 0), b2, voffB); PG8_STAGE(PG8_SB(0, 1), b2 + hstep, voffB); PG8_STAGE(PG8_SA(0, 0), a2, voffA);
;             PG8_WAIT_V(8); PG8_WAIT_L(0); PG8_BAR; PG8_MMA(1, 0, At, B0); PG8_MMA(1, 1, At, B1); PG8_BAR; PG8_SCHED;
.LBB0_102:
	ds_read_b128 v[160:163], v155
	ds_read_b128 v[164:167], v155 offset:1024
	ds_read_b128 v[168:171], v155 offset:2048
	ds_read_b128 v[172:175], v155 offset:3072
	ds_read_b128 v[176:179], v157
	ds_read_b128 v[180:183], v157 offset:1024
	ds_read_b128 v[184:187], v157 offset:2048
	ds_read_b128 v[188:191], v157 offset:3072
	s_add_u32 s62, s74, 0xfff80080
	s_addc_u32 s63, s75, -1
	s_cmp_eq_u32 s90, 28
	s_cselect_b32 s79, s10, s63
	s_cselect_b32 s78, s11, s62
	s_cselect_b32 s77, s51, s89
	s_cselect_b32 s76, s55, s88
	s_add_i32 m0, s61, 0xc000
	ds_read_b128 v[192:195], v159
	ds_read_b128 v[196:199], v159 offset:1024
	ds_read_b128 v[200:203], v159 offset:2048
	ds_read_b128 v[204:207], v159 offset:3072
	ds_read_b128 v[208:211], v159 offset:4096
	ds_read_b128 v[212:215], v159 offset:5120
	ds_read_b128 v[216:219], v159 offset:6144
	ds_read_b128 v[220:223], v159 offset:7168
	global_load_lds_dwordx4 v138, s[74:75]
	s_add_i32 m0, s61, 0xe000
	s_nop 0
	global_load_lds_dwordx4 v140, s[74:75]
	s_waitcnt vmcnt(8)
	s_waitcnt lgkmcnt(0)
	s_setprio 1
	s_barrier
	v_mfma_f32_16x16x32_bf16 v[124:127], v[160:163], v[192:195], v[124:127]
	v_mfma_f32_16x16x32_bf16 v[124:127], v[164:167], v[196:199], v[124:127]
	v_mfma_f32_16x16x32_bf16 v[108:111], v[160:163], v[200:203], v[108:111]
	v_mfma_f32_16x16x32_bf16 v[108:111], v[164:167], v[204:207], v[108:111]
	v_mfma_f32_16x16x32_bf16 v[92:95], v[160:163], v[208:211], v[92:95]
	v_mfma_f32_16x16x32_bf16 v[92:95], v[164:167], v[212:215], v[92:95]
	v_mfma_f32_16x16x32_bf16 v[76:79], v[160:163], v[216:219], v[76:79]
	v_mfma_f32_16x16x32_bf16 v[76:79], v[164:167], v[220:223], v[76:79]
	v_mfma_f32_16x16x32_bf16 v[72:75], v[168:171], v[216:219], v[72:75]
	v_mfma_f32_16x16x32_bf16 v[72:75], v[172:175], v[220:223], v[72:75]
	v_mfma_f32_16x16x32_bf16 v[88:91], v[168:171], v[208:211], v[88:91]
	v_mfma_f32_16x16x32_bf16 v[88:91], v[172:175], v[212:215], v[88:91]
	v_mfma_f32_16x16x32_bf16 v[104:107], v[168:171], v[200:203], v[104:107]
	v_mfma_f32_16x16x32_bf16 v[104:107], v[172:175], v[204:207], v[104:107]
	v_mfma_f32_16x16x32_bf16 v[120:123], v[168:171], v[192:195], v[120:123]
	v_mfma_f32_16x16x32_bf16 v[120:123], v[172:175], v[196:199], v[120:123]
	v_mfma_f32_16x16x32_bf16 v[116:119], v[176:179], v[192:195], v[116:119]
	v_mfma_f32_16x16x32_bf16 v[116:119], v[180:183], v[196:199], v[116:119]
	v_mfma_f32_16x16x32_bf16 v[100:103], v[176:179], v[200:203], v[100:103]
	v_mfma_f32_16x16x32_bf16 v[100:103], v[180:183], v[204:207], v[100:103]
	v_mfma_f32_16x16x32_bf16 v[84:87], v[176:179], v[208:211], v[84:87]
	v_mfma_f32_16x16x32_bf16 v[84:87], v[180:183], v[212:215], v[84:87]
	v_mfma_f32_16x16x32_bf16 v[68:71], v[176:179], v[216:219], v[68:71]
	v_mfma_f32_16x16x32_bf16 v[68:71], v[180:183], v[220:223], v[68:71]
	v_mfma_f32_16x16x32_bf16 v[64:67], v[184:187], v[216:219], v[64:67]
	v_mfma_f32_16x16x32_bf16 v[64:67], v[188:191], v[220:223], v[64:67]
	v_mfma_f32_16x16x32_bf16 v[80:83], v[184:187], v[208:211], v[80:83]
	v_mfma_f32_16x16x32_bf16 v[80:83], v[188:191], v[212:215], v[80:83]
	s_setprio 2
	s_barrier
	v_mfma_f32_16x16x32_bf16 v[96:99], v[184:187], v[200:203], v[96:99]
	v_mfma_f32_16x16x32_bf16 v[96:99], v[188:191], v[204:207], v[96:99]
	v_mfma_f32_16x16x32_bf16 v[112:115], v[184:187], v[192:195], v[112:115]
	v_mfma_f32_16x16x32_bf16 v[112:115], v[188:191], v[196:199], v[112:115]
	s_setprio 0
	s_add_i32 s62, s84, s35
	s_mov_b32 m0, s62
	ds_read_b128 v[192:195], v159 offset:16384
	ds_read_b128 v[196:199], v159 offset:17408
	ds_read_b128 v[200:203], v159 offset:18432
	ds_read_b128 v[204:207], v159 offset:19456
	ds_read_b128 v[208:211], v159 offset:20480
	ds_read_b128 v[212:215], v159 offset:21504
	ds_read_b128 v[216:219], v159 offset:22528
	ds_read_b128 v[220:223], v159 offset:23552
	global_load_lds_dwordx4 v130, s[76:77]
	s_add_i32 m0, s62, 0x2000
	s_add_u32 s92, s76, 0x80000
	s_addc_u32 s93, s77, 0
	s_add_i32 s62, s85, s35
	global_load_lds_dwordx4 v134, s[76:77]
	s_mov_b32 m0, s62
	s_nop 0
	global_load_lds_dwordx4 v130, s[92:93]
	s_add_i32 m0, s62, 0x2000
	s_nop 0
	global_load_lds_dwordx4 v134, s[92:93]
	s_mov_b32 m0, s61
	s_nop 0
	global_load_lds_dwordx4 v128, s[78:79]
	s_mov_b32 m0, s65
	s_nop 0
	global_load_lds_dwordx4 v132, s[78:79]
	s_waitcnt vmcnt(8)
	s_waitcnt lgkmcnt(0)
	s_setprio 1
	s_barrier
	v_mfma_f32_16x16x32_bf16 v[60:63], v[160:163], v[192:195], v[60:63]
	v_mfma_f32_16x16x32_bf16 v[60:63], v[164:167], v[196:199], v[60:63]
	v_mfma_f32_16x16x32_bf16 v[44:47], v[160:163], v[200:203], v[44:47]
	v_mfma_f32_16x16x32_bf16 v[44:47], v[164:167], v[204:207], v[44:47]
	v_mfma_f32_16x16x32_bf16 v[28:31], v[160:163], v[208:211], v[28:31]
	v_mfma_f32_16x16x32_bf16 v[28:31], v[164:167], v[212:215], v[28:31]
	v_mfma_f32_16x16x32_bf16 v[12:15], v[160:163], v[216:219], v[12:15]
	v_mfma_f32_16x16x32_bf16 v[12:15], v[164:167], v[220:223], v[12:15]
	v_mfma_f32_16x16x32_bf16 v[8:11], v[168:171], v[216:219], v[8:11]
	v_mfma_f32_16x16x32_bf16 v[8:11], v[172:175], v[220:223], v[8:11]
	v_mfma_f32_16x16x32_bf16 v[24:27], v[168:171], v[208:211], v[24:27]
	v_mfma_f32_16x16x32_bf16 v[24:27], v[172:175], v[212:215], v[24:27]
	v_mfma_f32_16x16x32_bf16 v[40:43], v[168:171], v[200:203], v[40:43]
	v_mfma_f32_16x16x32_bf16 v[40:43], v[172:175], v[204:207], v[40:43]
	v_mfma_f32_16x16x32_bf16 v[56:59], v[168:171], v[192:195], v[56:59]
	v_mfma_f32_16x16x32_bf16 v[56:59], v[172:175], v[196:199], v[56:59]
	v_mfma_f32_16x16x32_bf16 v[52:55], v[176:179], v[192:195], v[52:55]
	v_mfma_f32_16x16x32_bf16 v[52:55], v[180:183], v[196:199], v[52:55]
	v_mfma_f32_16x16x32_bf16 v[36:39], v[176:179], v[200:203], v[36:39]
	v_mfma_f32_16x16x32_bf16 v[36:39], v[180:183], v[204:207], v[36:39]
	v_mfma_f32_16x16x32_bf16 v[20:23], v[176:179], v[208:211], v[20:23]
	v_mfma_f32_16x16x32_bf16 v[20:23], v[180:183], v[212:215], v[20:23]
	v_mfma_f32_16x16x32_bf16 v[4:7], v[176:179], v[216:219], v[4:7]
	v_mfma_f32_16x16x32_bf16 v[4:7], v[180:183], v[220:223], v[4:7]
	v_mfma_f32_16x16x32_bf16 v[0:3], v[184:187], v[216:219], v[0:3]
	v_mfma_f32_16x16x32_bf16 v[0:3], v[188:191], v[220:223], v[0:3]
	v_mfma_f32_16x16x32_bf16 v[16:19], v[184:187], v[208:211], v[16:19]
	v_mfma_f32_16x16x32_bf16 v[16:19], v[188:191], v[212:215], v[16:19]
	s_setprio 2
	s_barrier
; #define PG8_STAGE(bufoff, gbase, voff) do { _Pragma("unroll") for (int _i = 0; _i < 2; ++_i) \
;         __builtin_amdgcn_global_load_lds((const unsigned*)((const char*)(gbase) + (voff)[_i]), (PG8_LAS unsigned*)(lds + (bufoff) + ldsw + _i * 8192), 16, 0, 0); } while (0)
; #define PG8_LDA(dst, b, h) do { _Pragma("unroll") for (int m = 0; m < 4; ++m) _Pragma("unroll") for (int k = 0; k < 2; ++k) dst[m][k] = *(const PG8_LAS bf16x8*)(lds + PG8_SA(b, h) + aoff + m * 2048 + k * 1024); } while (0)
; #define PG8_LDB(dst, b, h) do { _Pragma("unroll") for (int n = 0; n < 2; ++n) _Pragma("unroll") for (int k = 0; k < 2; ++k) dst[n][k] = *(const PG8_LAS bf16x8*)(lds + PG8_SB(b, h) + boff + n * 2048 + k * 1024); } while (0)
; #define PG8_MMA(ai, bj, At, Bt) do { __builtin_amdgcn_s_setprio(1); _Pragma("unroll") for (int m = 0; m < 4; ++m) _Pragma("unroll") for (int n = 0; n < 2; ++n) _Pragma("unroll") for (int k = 0; k < 2; ++k) \
;         acc[ai][bj][m][n] = __builtin_amdgcn_mfma_f32_16x16x32_bf16(Bt[n][k], At[m][k], acc[ai][bj][m][n], 0, 0, 0); __builtin_amdgcn_s_setprio(0); } while (0)
; #define PG8_WAIT_V(n) asm volatile("s_waitcnt vmcnt(" #n ")" ::: "memory")
; #define PG8_WAIT_L(n) asm volatile("s_waitcnt lgkmcnt(" #n ")" ::: "memory")
; #define PG8_BAR __builtin_amdgcn_s_barrier()
; #define PG8_SCHED __builtin_amdgcn_sched_barrier(0)
; template <class Epi, class Sched, bool ALIGN_EPI = false, bool SP2 = false>
; __device__ __forceinline__ void gemm_phase(PG8_LAS unsigned char* lds, const Gemm g, const Sched& S, const Epi& E) {
;     ...
;             PG8_WAIT_V(8); PG8_WAIT_L(0); PG8_BAR; PG8_MMA(1, 0, At, B0); PG8_MMA(1, 1, At, B1); PG8_BAR; PG8_SCHED;
;             PG8_LDB(B0, 1, 0); PG8_LDB(B1, 1, 1); PG8_SCHED; PG8_LDA(At, 1, 0); PG8_STAGE(PG8_SA(0, 1), a2 + hstep, voffA);
;             PG8_WAIT_V(8); PG8_WAIT_L(0); PG8_BAR; PG8_MMA(0, 0, At, B0); PG8_MMA(0, 1, At, B1); PG8_BAR; PG8_SCHED;
	v_mfma_f32_16x16x32_bf16 v[32:35], v[184:187], v[200:203], v[32:35]
	v_mfma_f32_16x16x32_bf16 v[32:35], v[188:191], v[204:207], v[32:35]
	v_mfma_f32_16x16x32_bf16 v[48:51], v[184:187], v[192:195], v[48:51]
	v_mfma_f32_16x16x32_bf16 v[48:51], v[188:191], v[196:199], v[48:51]
	s_setprio 0
	s_add_i32 s62, 0, 0x18000
	s_add_i32 s63, 0, 0x1c000
	v_add_u32_e32 v172, s62, v147
	v_add_u32_e32 v188, s63, v147
	ds_read_b128 v[160:163], v172
	ds_read_b128 v[164:167], v172 offset:1024
	ds_read_b128 v[168:171], v172 offset:2048
	ds_read_b128 v[172:175], v172 offset:3072
	ds_read_b128 v[176:179], v188
	ds_read_b128 v[180:183], v188 offset:1024
	ds_read_b128 v[184:187], v188 offset:2048
	ds_read_b128 v[188:191], v188 offset:3072
	s_mov_b64 s[100:101], s[78:79]
	s_add_u32 s78, s78, 0x80000
	s_addc_u32 s79, s79, 0
	s_mov_b32 m0, s66
	ds_read_b128 v[192:195], v159 offset:32768
	ds_read_b128 v[196:199], v159 offset:33792
	ds_read_b128 v[200:203], v159 offset:34816
	ds_read_b128 v[204:207], v159 offset:35840
	ds_read_b128 v[208:211], v159 offset:36864
	ds_read_b128 v[212:215], v159 offset:37888
	ds_read_b128 v[216:219], v159 offset:38912
	ds_read_b128 v[220:223], v159 offset:39936
	global_load_lds_dwordx4 v128, s[78:79]
	s_mov_b32 m0, s67
	s_nop 0
	global_load_lds_dwordx4 v132, s[78:79]
	s_waitcnt vmcnt(8)
	s_waitcnt lgkmcnt(0)
	s_setprio 1
	s_barrier
	v_mfma_f32_16x16x32_bf16 v[124:127], v[160:163], v[192:195], v[124:127]
	v_mfma_f32_16x16x32_bf16 v[124:127], v[164:167], v[196:199], v[124:127]
	v_mfma_f32_16x16x32_bf16 v[108:111], v[160:163], v[200:203], v[108:111]
	v_mfma_f32_16x16x32_bf16 v[108:111], v[164:167], v[204:207], v[108:111]
	v_mfma_f32_16x16x32_bf16 v[92:95], v[160:163], v[208:211], v[92:95]
	v_mfma_f32_16x16x32_bf16 v[92:95], v[164:167], v[212:215], v[92:95]
	v_mfma_f32_16x16x32_bf16 v[76:79], v[160:163], v[216:219], v[76:79]
	v_mfma_f32_16x16x32_bf16 v[76:79], v[164:167], v[220:223], v[76:79]
	v_mfma_f32_16x16x32_bf16 v[72:75], v[168:171], v[216:219], v[72:75]
	v_mfma_f32_16x16x32_bf16 v[72:75], v[172:175], v[220:223], v[72:75]
	v_mfma_f32_16x16x32_bf16 v[88:91], v[168:171], v[208:211], v[88:91]
	v_mfma_f32_16x16x32_bf16 v[88:91], v[172:175], v[212:215], v[88:91]
	v_mfma_f32_16x16x32_bf16 v[104:107], v[168:171], v[200:203], v[104:107]
	v_mfma_f32_16x16x32_bf16 v[104:107], v[172:175], v[204:207], v[104:107]
	v_mfma_f32_16x16x32_bf16 v[120:123], v[168:171], v[192:195], v[120:123]
	v_mfma_f32_16x16x32_bf16 v[120:123], v[172:175], v[196:199], v[120:123]
	v_mfma_f32_16x16x32_bf16 v[116:119], v[176:179], v[192:195], v[116:119]
	v_mfma_f32_16x16x32_bf16 v[116:119], v[180:183], v[196:199], v[116:119]
	v_mfma_f32_16x16x32_bf16 v[100:103], v[176:179], v[200:203], v[100:103]
	v_mfma_f32_16x16x32_bf16 v[100:103], v[180:183], v[204:207], v[100:103]
	v_mfma_f32_16x16x32_bf16 v[84:87], v[176:179], v[208:211], v[84:87]
	v_mfma_f32_16x16x32_bf16 v[84:87], v[180:183], v[212:215], v[84:87]
	v_mfma_f32_16x16x32_bf16 v[68:71], v[176:179], v[216:219], v[68:71]
	v_mfma_f32_16x16x32_bf16 v[68:71], v[180:183], v[220:223], v[68:71]
	v_mfma_f32_16x16x32_bf16 v[64:67], v[184:187], v[216:219], v[64:67]
	v_mfma_f32_16x16x32_bf16 v[64:67], v[188:191], v[220:223], v[64:67]
	v_mfma_f32_16x16x32_bf16 v[80:83], v[184:187], v[208:211], v[80:83]
	v_mfma_f32_16x16x32_bf16 v[80:83], v[188:191], v[212:215], v[80:83]
	s_setprio 2
	s_barrier
; #define PG8_STAGE(bufoff, gbase, voff) do { _Pragma("unroll") for (int _i = 0; _i < 2; ++_i) \
;         __builtin_amdgcn_global_load_lds((const unsigned*)((const char*)(gbase) + (voff)[_i]), (PG8_LAS unsigned*)(lds + (bufoff) + ldsw + _i * 8192), 16, 0, 0); } while (0)
; #define PG8_LDA(dst, b, h) do { _Pragma("unroll") for (int m = 0; m < 4; ++m) _Pragma("unroll") for (int k = 0; k < 2; ++k) dst[m][k] = *(const PG8_LAS bf16x8*)(lds + PG8_SA(b, h) + aoff + m * 2048 + k * 1024); } while (0)
; #define PG8_MMA(ai, bj, At, Bt) do { __builtin_amdgcn_s_setprio(1); _Pragma("unroll") for (int m = 0; m < 4; ++m) _Pragma("unroll") for (int n = 0; n < 2; ++n) _Pragma("unroll") for (int k = 0; k < 2; ++k) \
;         acc[ai][bj][m][n] = __builtin_amdgcn_mfma_f32_16x16x32_bf16(Bt[n][k], At[m][k], acc[ai][bj][m][n], 0, 0, 0); __builtin_amdgcn_s_setprio(0); } while (0)
; #define PG8_WAIT_V(n) asm volatile("s_waitcnt vmcnt(" #n ")" ::: "memory")
; #define PG8_WAIT_L(n) asm volatile("s_waitcnt lgkmcnt(" #n ")" ::: "memory")
; #define PG8_BAR __builtin_amdgcn_s_barrier()
; #define PG8_SCHED __builtin_amdgcn_sched_barrier(0)
; template <class Epi, class Sched, bool ALIGN_EPI = false, bool SP2 = false>
; __device__ __forceinline__ void gemm_phase(PG8_LAS unsigned char* lds, const Gemm g, const Sched& S, const Epi& E) {
;     ...
;             PG8_WAIT_V(8); PG8_WAIT_L(0); PG8_BAR; PG8_MMA(0, 0, At, B0); PG8_MMA(0, 1, At, B1); PG8_BAR; PG8_SCHED;
;             PG8_LDA(At, 1, 1); PG8_STAGE(PG8_SB(1, 0), b3, voffB); PG8_STAGE(PG8_SB(1, 1), b3 + hstep, voffB); PG8_STAGE(PG8_SA(1, 0), a3, voffA);
;             PG8_WAIT_V(8); PG8_WAIT_L(0); PG8_BAR; PG8_MMA(1, 0, At, B0); PG8_MMA(1, 1, At, B1); PG8_BAR; PG8_SCHED;
;     ...
;         if constexpr (ALIGN_EPI) { if (wr == 0) PG8_BAR; }
	v_mfma_f32_16x16x32_bf16 v[96:99], v[184:187], v[200:203], v[96:99]
	v_mfma_f32_16x16x32_bf16 v[96:99], v[188:191], v[204:207], v[96:99]
	v_mfma_f32_16x16x32_bf16 v[112:115], v[184:187], v[192:195], v[112:115]
	v_mfma_f32_16x16x32_bf16 v[112:115], v[188:191], v[196:199], v[112:115]
	s_setprio 0
	s_add_i32 s62, s62, s35
	s_add_i32 m0, s62, 0xffffff80
	ds_read_b128 v[192:195], v159 offset:49152
	ds_read_b128 v[196:199], v159 offset:50176
	ds_read_b128 v[200:203], v159 offset:51200
	ds_read_b128 v[204:207], v159 offset:52224
	ds_read_b128 v[208:211], v159 offset:53248
	ds_read_b128 v[212:215], v159 offset:54272
	ds_read_b128 v[216:219], v159 offset:55296
	ds_read_b128 v[220:223], v159 offset:56320
	global_load_lds_dwordx4 v130, s[76:77] offset:128
	s_add_i32 m0, s62, 0x1f80
	s_mov_b64 s[98:99], s[76:77]
	s_add_u32 s76, s76, 0x80080
	s_addc_u32 s77, s77, 0
	s_add_i32 s62, s63, s35
	global_load_lds_dwordx4 v134, s[98:99] offset:128
	s_mov_b32 m0, s62
	s_nop 0
	global_load_lds_dwordx4 v130, s[76:77]
	s_add_i32 m0, s62, 0x2000
	s_nop 0
	global_load_lds_dwordx4 v134, s[76:77]
	s_add_i32 m0, s81, 0xffffff80
	s_nop 0
	global_load_lds_dwordx4 v128, s[100:101] offset:128
	s_add_i32 m0, s82, 0xffffff80
	s_nop 0
	global_load_lds_dwordx4 v132, s[100:101] offset:128
	s_waitcnt vmcnt(8)
	s_waitcnt lgkmcnt(0)
	s_setprio 1
	s_barrier
	v_mfma_f32_16x16x32_bf16 v[60:63], v[160:163], v[192:195], v[60:63]
	v_mfma_f32_16x16x32_bf16 v[60:63], v[164:167], v[196:199], v[60:63]
	v_mfma_f32_16x16x32_bf16 v[44:47], v[160:163], v[200:203], v[44:47]
	v_mfma_f32_16x16x32_bf16 v[44:47], v[164:167], v[204:207], v[44:47]
	v_mfma_f32_16x16x32_bf16 v[28:31], v[160:163], v[208:211], v[28:31]
	v_mfma_f32_16x16x32_bf16 v[28:31], v[164:167], v[212:215], v[28:31]
	v_mfma_f32_16x16x32_bf16 v[12:15], v[160:163], v[216:219], v[12:15]
	v_mfma_f32_16x16x32_bf16 v[12:15], v[164:167], v[220:223], v[12:15]
	v_mfma_f32_16x16x32_bf16 v[8:11], v[168:171], v[216:219], v[8:11]
	v_mfma_f32_16x16x32_bf16 v[8:11], v[172:175], v[220:223], v[8:11]
	v_mfma_f32_16x16x32_bf16 v[24:27], v[168:171], v[208:211], v[24:27]
	v_mfma_f32_16x16x32_bf16 v[24:27], v[172:175], v[212:215], v[24:27]
	v_mfma_f32_16x16x32_bf16 v[40:43], v[168:171], v[200:203], v[40:43]
	v_mfma_f32_16x16x32_bf16 v[40:43], v[172:175], v[204:207], v[40:43]
	v_mfma_f32_16x16x32_bf16 v[56:59], v[168:171], v[192:195], v[56:59]
	v_mfma_f32_16x16x32_bf16 v[56:59], v[172:175], v[196:199], v[56:59]
	v_mfma_f32_16x16x32_bf16 v[52:55], v[176:179], v[192:195], v[52:55]
	v_mfma_f32_16x16x32_bf16 v[52:55], v[180:183], v[196:199], v[52:55]
	v_mfma_f32_16x16x32_bf16 v[36:39], v[176:179], v[200:203], v[36:39]
	v_mfma_f32_16x16x32_bf16 v[36:39], v[180:183], v[204:207], v[36:39]
	v_mfma_f32_16x16x32_bf16 v[20:23], v[176:179], v[208:211], v[20:23]
	v_mfma_f32_16x16x32_bf16 v[20:23], v[180:183], v[212:215], v[20:23]
	v_mfma_f32_16x16x32_bf16 v[4:7], v[176:179], v[216:219], v[4:7]
	v_mfma_f32_16x16x32_bf16 v[4:7], v[180:183], v[220:223], v[4:7]
	v_mfma_f32_16x16x32_bf16 v[0:3], v[184:187], v[216:219], v[0:3]
	v_mfma_f32_16x16x32_bf16 v[0:3], v[188:191], v[220:223], v[0:3]
	v_mfma_f32_16x16x32_bf16 v[16:19], v[184:187], v[208:211], v[16:19]
	v_mfma_f32_16x16x32_bf16 v[16:19], v[188:191], v[212:215], v[16:19]
	s_setprio 2
	s_barrier
	v_mfma_f32_16x16x32_bf16 v[32:35], v[184:187], v[200:203], v[32:35]
	v_mfma_f32_16x16x32_bf16 v[32:35], v[188:191], v[204:207], v[32:35]
	v_mfma_f32_16x16x32_bf16 v[48:51], v[184:187], v[192:195], v[48:51]
	v_mfma_f32_16x16x32_bf16 v[48:51], v[188:191], v[196:199], v[48:51]
	s_setprio 0
	s_add_i32 s90, s90, 2
	s_add_u32 s74, s74, 0x100
	s_addc_u32 s75, s75, 0
	s_add_u32 s88, s88, 0x100
	s_addc_u32 s89, s89, 0
	s_cmp_gt_u32 s90, 29
	s_cbranch_scc0 .LBB0_102
	s_and_b64 vcc, exec, s[22:23]
	s_cbranch_vccz .LBB0_105
	s_barrier

; #define PG8_STAGE(bufoff, gbase, voff) do { _Pragma("unroll") for (int _i = 0; _i < 2; ++_i) \
;         __builtin_amdgcn_global_load_lds((const unsigned*)((const char*)(gbase) + (voff)[_i]), (PG8_LAS unsigned*)(lds + (bufoff) + ldsw + _i * 8192), 16, 0, 0); } while (0)
; #define PG8_LDA(dst, b, h) do { _Pragma("unroll") for (int m = 0; m < 4; ++m) _Pragma("unroll") for (int k = 0; k < 2; ++k) dst[m][k] = *(const PG8_LAS bf16x8*)(lds + PG8_SA(b, h) + aoff + m * 2048 + k * 1024); } while (0)
; #define PG8_LDB(dst, b, h) do { _Pragma("unroll") for (int n = 0; n < 2; ++n) _Pragma("unroll") for (int k = 0; k < 2; ++k) dst[n][k] = *(const PG8_LAS bf16x8*)(lds + PG8_SB(b, h) + boff + n * 2048 + k * 1024); } while (0)
; #define PG8_MMA(ai, bj, At, Bt) do { __builtin_amdgcn_s_setprio(1); _Pragma("unroll") for (int m = 0; m < 4; ++m) _Pragma("unroll") for (int n = 0; n < 2; ++n) _Pragma("unroll") for (int k = 0; k < 2; ++k) \
;         acc[ai][bj][m][n] = __builtin_amdgcn_mfma_f32_16x16x32_bf16(Bt[n][k], At[m][k], acc[ai][bj][m][n], 0, 0, 0); __builtin_amdgcn_s_setprio(0); } while (0)
; #define PG8_WAIT_V(n) asm volatile("s_waitcnt vmcnt(" #n ")" ::: "memory")
; #define PG8_WAIT_L(n) asm volatile("s_waitcnt lgkmcnt(" #n ")" ::: "memory")
; template <class Epi, class Sched, bool ALIGN_EPI = false, bool SP2 = false>
; __device__ __forceinline__ void gemm_phase(PG8_LAS unsigned char* lds, const Gemm g, const Sched& S, const Epi& E) {
;     ...
;             const bool last = (t == nt - 2);
;             const char* a1 = cA + (size_t)(t + 1) * kstep;
;             const char* a2 = last ? nA : cA + (size_t)(t + 2) * kstep; const char* b2 = last ? nB : cB + (size_t)(t + 2) * kstep;
;             const char* a3 = a2 + kstep; const char* b3 = b2 + kstep;
;             if (last && has_next) S.a_ready(nxt);
;             if constexpr (SP2) {
;             PG8_LDB(B0, 0, 0); PG8_LDB(B1, 0, 1); PG8_SCHED; PG8_LDA(At, 0, 0); PG8_STAGE(PG8_SA(1, 1), a1 + hstep, voffA);
;             PG8_WAIT_V(8); PG8_WAIT_L(0); PG8_BAR; PG8_MMA(0, 0, At, B0); PG8_MMA(0, 1, At, B1); PG8_BAR; PG8_SCHED;
;             PG8_LDA(At, 0, 1); PG8_STAGE(PG8_SB(0, 0), b2, voffB); PG8_STAGE(PG8_SB(0, 1), b2 + hstep, voffB); PG8_STAGE(PG8_SA(0, 0), a2, voffA);
;             PG8_WAIT_V(8); PG8_WAIT_L(0); PG8_BAR; PG8_MMA(1, 0, At, B0); PG8_MMA(1, 1, At, B1); PG8_BAR; PG8_SCHED;
.LBB0_179:
	ds_read_b128 v[144:147], v155
	ds_read_b128 v[160:163], v155 offset:1024
	ds_read_b128 v[164:167], v155 offset:2048
	ds_read_b128 v[168:171], v155 offset:3072
	ds_read_b128 v[172:175], v156
	ds_read_b128 v[176:179], v156 offset:1024
	ds_read_b128 v[180:183], v156 offset:2048
	ds_read_b128 v[184:187], v156 offset:3072
	s_add_u32 s62, s76, 0xffea0080
	s_addc_u32 s63, s77, -1
	s_cmpk_eq_i32 s92, 0x54
	s_cselect_b32 s81, s7, s63
	s_cselect_b32 s80, s6, s62
	s_cselect_b32 s79, s75, s91
	s_cselect_b32 s78, s74, s50
	s_add_i32 m0, s52, 0xc000
	ds_read_b128 v[188:191], v157
	ds_read_b128 v[192:195], v157 offset:1024
	ds_read_b128 v[196:199], v157 offset:2048
	ds_read_b128 v[200:203], v157 offset:3072
	ds_read_b128 v[204:207], v157 offset:4096
	ds_read_b128 v[208:211], v157 offset:5120
	ds_read_b128 v[212:215], v157 offset:6144
	ds_read_b128 v[216:219], v157 offset:7168
	global_load_lds_dwordx4 v136, s[76:77]
	s_add_i32 m0, s52, 0xe000
	s_nop 0
	global_load_lds_dwordx4 v138, s[76:77]
	s_waitcnt vmcnt(8)
	s_waitcnt lgkmcnt(0)
	s_setprio 1
	s_barrier
	v_mfma_f32_16x16x32_bf16 v[124:127], v[144:147], v[188:191], v[124:127]
	v_mfma_f32_16x16x32_bf16 v[124:127], v[160:163], v[192:195], v[124:127]
	v_mfma_f32_16x16x32_bf16 v[108:111], v[144:147], v[196:199], v[108:111]
	v_mfma_f32_16x16x32_bf16 v[108:111], v[160:163], v[200:203], v[108:111]
	v_mfma_f32_16x16x32_bf16 v[92:95], v[144:147], v[204:207], v[92:95]
	v_mfma_f32_16x16x32_bf16 v[92:95], v[160:163], v[208:211], v[92:95]
	v_mfma_f32_16x16x32_bf16 v[76:79], v[144:147], v[212:215], v[76:79]
	v_mfma_f32_16x16x32_bf16 v[76:79], v[160:163], v[216:219], v[76:79]
	v_mfma_f32_16x16x32_bf16 v[72:75], v[164:167], v[212:215], v[72:75]
	v_mfma_f32_16x16x32_bf16 v[72:75], v[168:171], v[216:219], v[72:75]
	v_mfma_f32_16x16x32_bf16 v[88:91], v[164:167], v[204:207], v[88:91]
	v_mfma_f32_16x16x32_bf16 v[88:91], v[168:171], v[208:211], v[88:91]
	v_mfma_f32_16x16x32_bf16 v[104:107], v[164:167], v[196:199], v[104:107]
	v_mfma_f32_16x16x32_bf16 v[104:107], v[168:171], v[200:203], v[104:107]
	v_mfma_f32_16x16x32_bf16 v[120:123], v[164:167], v[188:191], v[120:123]
	v_mfma_f32_16x16x32_bf16 v[120:123], v[168:171], v[192:195], v[120:123]
	v_mfma_f32_16x16x32_bf16 v[116:119], v[172:175], v[188:191], v[116:119]
	v_mfma_f32_16x16x32_bf16 v[116:119], v[176:179], v[192:195], v[116:119]
	v_mfma_f32_16x16x32_bf16 v[100:103], v[172:175], v[196:199], v[100:103]
	v_mfma_f32_16x16x32_bf16 v[100:103], v[176:179], v[200:203], v[100:103]
	v_mfma_f32_16x16x32_bf16 v[84:87], v[172:175], v[204:207], v[84:87]
	v_mfma_f32_16x16x32_bf16 v[84:87], v[176:179], v[208:211], v[84:87]
	v_mfma_f32_16x16x32_bf16 v[68:71], v[172:175], v[212:215], v[68:71]
	v_mfma_f32_16x16x32_bf16 v[68:71], v[176:179], v[216:219], v[68:71]
	v_mfma_f32_16x16x32_bf16 v[64:67], v[180:183], v[212:215], v[64:67]
	v_mfma_f32_16x16x32_bf16 v[64:67], v[184:187], v[216:219], v[64:67]
	v_mfma_f32_16x16x32_bf16 v[80:83], v[180:183], v[204:207], v[80:83]
	v_mfma_f32_16x16x32_bf16 v[80:83], v[184:187], v[208:211], v[80:83]
	s_setprio 2
	s_barrier
	v_mfma_f32_16x16x32_bf16 v[96:99], v[180:183], v[196:199], v[96:99]
	v_mfma_f32_16x16x32_bf16 v[96:99], v[184:187], v[200:203], v[96:99]
	v_mfma_f32_16x16x32_bf16 v[112:115], v[180:183], v[188:191], v[112:115]
	v_mfma_f32_16x16x32_bf16 v[112:115], v[184:187], v[192:195], v[112:115]
	s_setprio 0
	s_add_i32 s62, s86, s35
	s_mov_b32 m0, s62
	ds_read_b128 v[188:191], v157 offset:16384
	ds_read_b128 v[192:195], v157 offset:17408
	ds_read_b128 v[196:199], v157 offset:18432
	ds_read_b128 v[200:203], v157 offset:19456
	ds_read_b128 v[204:207], v157 offset:20480
	ds_read_b128 v[208:211], v157 offset:21504
	ds_read_b128 v[212:215], v157 offset:22528
	ds_read_b128 v[216:219], v157 offset:23552
	global_load_lds_dwordx4 v130, s[78:79]
	s_add_i32 m0, s62, 0x2000
	s_add_u32 s94, s78, 0x160000
	s_addc_u32 s95, s79, 0
	s_add_i32 s62, s87, s35
	global_load_lds_dwordx4 v134, s[78:79]
	s_mov_b32 m0, s62
	s_nop 0
	global_load_lds_dwordx4 v130, s[94:95]
	s_add_i32 m0, s62, 0x2000
	s_nop 0
	global_load_lds_dwordx4 v134, s[94:95]
	s_mov_b32 m0, s52
	s_nop 0
	global_load_lds_dwordx4 v128, s[80:81]
	s_mov_b32 m0, s53
	s_nop 0
	global_load_lds_dwordx4 v132, s[80:81]
	s_waitcnt vmcnt(8)
	s_waitcnt lgkmcnt(0)
	s_setprio 1
	s_barrier
	v_mfma_f32_16x16x32_bf16 v[60:63], v[144:147], v[188:191], v[60:63]
	v_mfma_f32_16x16x32_bf16 v[60:63], v[160:163], v[192:195], v[60:63]
	v_mfma_f32_16x16x32_bf16 v[44:47], v[144:147], v[196:199], v[44:47]
	v_mfma_f32_16x16x32_bf16 v[44:47], v[160:163], v[200:203], v[44:47]
	v_mfma_f32_16x16x32_bf16 v[28:31], v[144:147], v[204:207], v[28:31]
	v_mfma_f32_16x16x32_bf16 v[28:31], v[160:163], v[208:211], v[28:31]
	v_mfma_f32_16x16x32_bf16 v[12:15], v[144:147], v[212:215], v[12:15]
	v_mfma_f32_16x16x32_bf16 v[12:15], v[160:163], v[216:219], v[12:15]
	v_mfma_f32_16x16x32_bf16 v[8:11], v[164:167], v[212:215], v[8:11]
	v_mfma_f32_16x16x32_bf16 v[8:11], v[168:171], v[216:219], v[8:11]
	v_mfma_f32_16x16x32_bf16 v[24:27], v[164:167], v[204:207], v[24:27]
	v_mfma_f32_16x16x32_bf16 v[24:27], v[168:171], v[208:211], v[24:27]
	v_mfma_f32_16x16x32_bf16 v[40:43], v[164:167], v[196:199], v[40:43]
	v_mfma_f32_16x16x32_bf16 v[40:43], v[168:171], v[200:203], v[40:43]
	v_mfma_f32_16x16x32_bf16 v[56:59], v[164:167], v[188:191], v[56:59]
	v_mfma_f32_16x16x32_bf16 v[56:59], v[168:171], v[192:195], v[56:59]
	v_mfma_f32_16x16x32_bf16 v[52:55], v[172:175], v[188:191], v[52:55]
	v_mfma_f32_16x16x32_bf16 v[52:55], v[176:179], v[192:195], v[52:55]
	v_mfma_f32_16x16x32_bf16 v[36:39], v[172:175], v[196:199], v[36:39]
	v_mfma_f32_16x16x32_bf16 v[36:39], v[176:179], v[200:203], v[36:39]
	v_mfma_f32_16x16x32_bf16 v[20:23], v[172:175], v[204:207], v[20:23]
	v_mfma_f32_16x16x32_bf16 v[20:23], v[176:179], v[208:211], v[20:23]
	v_mfma_f32_16x16x32_bf16 v[4:7], v[172:175], v[212:215], v[4:7]
	v_mfma_f32_16x16x32_bf16 v[4:7], v[176:179], v[216:219], v[4:7]
	v_mfma_f32_16x16x32_bf16 v[0:3], v[180:183], v[212:215], v[0:3]
	v_mfma_f32_16x16x32_bf16 v[0:3], v[184:187], v[216:219], v[0:3]
	v_mfma_f32_16x16x32_bf16 v[16:19], v[180:183], v[204:207], v[16:19]
	v_mfma_f32_16x16x32_bf16 v[16:19], v[184:187], v[208:211], v[16:19]
	s_setprio 2
	s_barrier
; #define PG8_STAGE(bufoff, gbase, voff) do { _Pragma("unroll") for (int _i = 0; _i < 2; ++_i) \
;         __builtin_amdgcn_global_load_lds((const unsigned*)((const char*)(gbase) + (voff)[_i]), (PG8_LAS unsigned*)(lds + (bufoff) + ldsw + _i * 8192), 16, 0, 0); } while (0)
; #define PG8_LDA(dst, b, h) do { _Pragma("unroll") for (int m = 0; m < 4; ++m) _Pragma("unroll") for (int k = 0; k < 2; ++k) dst[m][k] = *(const PG8_LAS bf16x8*)(lds + PG8_SA(b, h) + aoff + m * 2048 + k * 1024); } while (0)
; #define PG8_LDB(dst, b, h) do { _Pragma("unroll") for (int n = 0; n < 2; ++n) _Pragma("unroll") for (int k = 0; k < 2; ++k) dst[n][k] = *(const PG8_LAS bf16x8*)(lds + PG8_SB(b, h) + boff + n * 2048 + k * 1024); } while (0)
; #define PG8_MMA(ai, bj, At, Bt) do { __builtin_amdgcn_s_setprio(1); _Pragma("unroll") for (int m = 0; m < 4; ++m) _Pragma("unroll") for (int n = 0; n < 2; ++n) _Pragma("unroll") for (int k = 0; k < 2; ++k) \
;         acc[ai][bj][m][n] = __builtin_amdgcn_mfma_f32_16x16x32_bf16(Bt[n][k], At[m][k], acc[ai][bj][m][n], 0, 0, 0); __builtin_amdgcn_s_setprio(0); } while (0)
; #define PG8_WAIT_V(n) asm volatile("s_waitcnt vmcnt(" #n ")" ::: "memory")
; #define PG8_WAIT_L(n) asm volatile("s_waitcnt lgkmcnt(" #n ")" ::: "memory")
; #define PG8_BAR __builtin_amdgcn_s_barrier()
; #define PG8_SCHED __builtin_amdgcn_sched_barrier(0)
; template <class Epi, class Sched, bool ALIGN_EPI = false, bool SP2 = false>
; __device__ __forceinline__ void gemm_phase(PG8_LAS unsigned char* lds, const Gemm g, const Sched& S, const Epi& E) {
;     ...
;             PG8_WAIT_V(8); PG8_WAIT_L(0); PG8_BAR; PG8_MMA(1, 0, At, B0); PG8_MMA(1, 1, At, B1); PG8_BAR; PG8_SCHED;
;             PG8_LDB(B0, 1, 0); PG8_LDB(B1, 1, 1); PG8_SCHED; PG8_LDA(At, 1, 0); PG8_STAGE(PG8_SA(0, 1), a2 + hstep, voffA);
;             PG8_WAIT_V(8); PG8_WAIT_L(0); PG8_BAR; PG8_MMA(0, 0, At, B0); PG8_MMA(0, 1, At, B1); PG8_BAR; PG8_SCHED;
	v_mfma_f32_16x16x32_bf16 v[32:35], v[180:183], v[196:199], v[32:35]
	v_mfma_f32_16x16x32_bf16 v[32:35], v[184:187], v[200:203], v[32:35]
	v_mfma_f32_16x16x32_bf16 v[48:51], v[180:183], v[188:191], v[48:51]
	v_mfma_f32_16x16x32_bf16 v[48:51], v[184:187], v[192:195], v[48:51]
	s_setprio 0
	s_add_i32 s62, 0, 0x18000
	v_add_u32_e32 v159, s62, v153
	s_add_i32 s63, 0, 0x1c000
	ds_read_b128 v[144:147], v159
	ds_read_b128 v[160:163], v159 offset:1024
	ds_read_b128 v[164:167], v159 offset:2048
	ds_read_b128 v[168:171], v159 offset:3072
	v_add_u32_e32 v159, s63, v153
	ds_read_b128 v[172:175], v159
	ds_read_b128 v[176:179], v159 offset:1024
	ds_read_b128 v[180:183], v159 offset:2048
	ds_read_b128 v[184:187], v159 offset:3072
	s_mov_b64 s[100:101], s[80:81]
	s_add_u32 s80, s80, 0x160000
	s_addc_u32 s81, s81, 0
	s_mov_b32 m0, s61
	ds_read_b128 v[188:191], v157 offset:32768
	ds_read_b128 v[192:195], v157 offset:33792
	ds_read_b128 v[196:199], v157 offset:34816
	ds_read_b128 v[200:203], v157 offset:35840
	ds_read_b128 v[204:207], v157 offset:36864
	ds_read_b128 v[208:211], v157 offset:37888
	ds_read_b128 v[212:215], v157 offset:38912
	ds_read_b128 v[216:219], v157 offset:39936
	global_load_lds_dwordx4 v128, s[80:81]
	s_mov_b32 m0, s65
	s_nop 0
	global_load_lds_dwordx4 v132, s[80:81]
	s_waitcnt vmcnt(8)
	s_waitcnt lgkmcnt(0)
	s_setprio 1
	s_barrier
	v_mfma_f32_16x16x32_bf16 v[124:127], v[144:147], v[188:191], v[124:127]
	v_mfma_f32_16x16x32_bf16 v[124:127], v[160:163], v[192:195], v[124:127]
	v_mfma_f32_16x16x32_bf16 v[108:111], v[144:147], v[196:199], v[108:111]
	v_mfma_f32_16x16x32_bf16 v[108:111], v[160:163], v[200:203], v[108:111]
	v_mfma_f32_16x16x32_bf16 v[92:95], v[144:147], v[204:207], v[92:95]
	v_mfma_f32_16x16x32_bf16 v[92:95], v[160:163], v[208:211], v[92:95]
	v_mfma_f32_16x16x32_bf16 v[76:79], v[144:147], v[212:215], v[76:79]
	v_mfma_f32_16x16x32_bf16 v[76:79], v[160:163], v[216:219], v[76:79]
	v_mfma_f32_16x16x32_bf16 v[72:75], v[164:167], v[212:215], v[72:75]
	v_mfma_f32_16x16x32_bf16 v[72:75], v[168:171], v[216:219], v[72:75]
	v_mfma_f32_16x16x32_bf16 v[88:91], v[164:167], v[204:207], v[88:91]
	v_mfma_f32_16x16x32_bf16 v[88:91], v[168:171], v[208:211], v[88:91]
	v_mfma_f32_16x16x32_bf16 v[104:107], v[164:167], v[196:199], v[104:107]
	v_mfma_f32_16x16x32_bf16 v[104:107], v[168:171], v[200:203], v[104:107]
	v_mfma_f32_16x16x32_bf16 v[120:123], v[164:167], v[188:191], v[120:123]
	v_mfma_f32_16x16x32_bf16 v[120:123], v[168:171], v[192:195], v[120:123]
	v_mfma_f32_16x16x32_bf16 v[116:119], v[172:175], v[188:191], v[116:119]
	v_mfma_f32_16x16x32_bf16 v[116:119], v[176:179], v[192:195], v[116:119]
	v_mfma_f32_16x16x32_bf16 v[100:103], v[172:175], v[196:199], v[100:103]
	v_mfma_f32_16x16x32_bf16 v[100:103], v[176:179], v[200:203], v[100:103]
	v_mfma_f32_16x16x32_bf16 v[84:87], v[172:175], v[204:207], v[84:87]
	v_mfma_f32_16x16x32_bf16 v[84:87], v[176:179], v[208:211], v[84:87]
	v_mfma_f32_16x16x32_bf16 v[68:71], v[172:175], v[212:215], v[68:71]
	v_mfma_f32_16x16x32_bf16 v[68:71], v[176:179], v[216:219], v[68:71]
	v_mfma_f32_16x16x32_bf16 v[64:67], v[180:183], v[212:215], v[64:67]
	v_mfma_f32_16x16x32_bf16 v[64:67], v[184:187], v[216:219], v[64:67]
	v_mfma_f32_16x16x32_bf16 v[80:83], v[180:183], v[204:207], v[80:83]
	v_mfma_f32_16x16x32_bf16 v[80:83], v[184:187], v[208:211], v[80:83]
	s_setprio 2
	s_barrier
; #define PG8_STAGE(bufoff, gbase, voff) do { _Pragma("unroll") for (int _i = 0; _i < 2; ++_i) \
;         __builtin_amdgcn_global_load_lds((const unsigned*)((const char*)(gbase) + (voff)[_i]), (PG8_LAS unsigned*)(lds + (bufoff) + ldsw + _i * 8192), 16, 0, 0); } while (0)
; #define PG8_LDA(dst, b, h) do { _Pragma("unroll") for (int m = 0; m < 4; ++m) _Pragma("unroll") for (int k = 0; k < 2; ++k) dst[m][k] = *(const PG8_LAS bf16x8*)(lds + PG8_SA(b, h) + aoff + m * 2048 + k * 1024); } while (0)
; #define PG8_MMA(ai, bj, At, Bt) do { __builtin_amdgcn_s_setprio(1); _Pragma("unroll") for (int m = 0; m < 4; ++m) _Pragma("unroll") for (int n = 0; n < 2; ++n) _Pragma("unroll") for (int k = 0; k < 2; ++k) \
;         acc[ai][bj][m][n] = __builtin_amdgcn_mfma_f32_16x16x32_bf16(Bt[n][k], At[m][k], acc[ai][bj][m][n], 0, 0, 0); __builtin_amdgcn_s_setprio(0); } while (0)
; #define PG8_WAIT_V(n) asm volatile("s_waitcnt vmcnt(" #n ")" ::: "memory")
; #define PG8_WAIT_L(n) asm volatile("s_waitcnt lgkmcnt(" #n ")" ::: "memory")
; #define PG8_BAR __builtin_amdgcn_s_barrier()
; #define PG8_SCHED __builtin_amdgcn_sched_barrier(0)
; template <class Epi, class Sched, bool ALIGN_EPI = false, bool SP2 = false>
; __device__ __forceinline__ void gemm_phase(PG8_LAS unsigned char* lds, const Gemm g, const Sched& S, const Epi& E) {
;     ...
;             PG8_WAIT_V(8); PG8_WAIT_L(0); PG8_BAR; PG8_MMA(0, 0, At, B0); PG8_MMA(0, 1, At, B1); PG8_BAR; PG8_SCHED;
;             PG8_LDA(At, 1, 1); PG8_STAGE(PG8_SB(1, 0), b3, voffB); PG8_STAGE(PG8_SB(1, 1), b3 + hstep, voffB); PG8_STAGE(PG8_SA(1, 0), a3, voffA);
;             PG8_WAIT_V(8); PG8_WAIT_L(0); PG8_BAR; PG8_MMA(1, 0, At, B0); PG8_MMA(1, 1, At, B1); PG8_BAR; PG8_SCHED;
;     ...
;         if constexpr (ALIGN_EPI) { if (wr == 0) PG8_BAR; }
	v_mfma_f32_16x16x32_bf16 v[96:99], v[180:183], v[196:199], v[96:99]
	v_mfma_f32_16x16x32_bf16 v[96:99], v[184:187], v[200:203], v[96:99]
	v_mfma_f32_16x16x32_bf16 v[112:115], v[180:183], v[188:191], v[112:115]
	v_mfma_f32_16x16x32_bf16 v[112:115], v[184:187], v[192:195], v[112:115]
	s_setprio 0
	s_add_i32 s62, s62, s35
	s_add_i32 m0, s62, 0xffffff80
	ds_read_b128 v[188:191], v157 offset:49152
	ds_read_b128 v[192:195], v157 offset:50176
	ds_read_b128 v[196:199], v157 offset:51200
	ds_read_b128 v[200:203], v157 offset:52224
	ds_read_b128 v[204:207], v157 offset:53248
	ds_read_b128 v[208:211], v157 offset:54272
	ds_read_b128 v[212:215], v157 offset:55296
	ds_read_b128 v[216:219], v157 offset:56320
	global_load_lds_dwordx4 v130, s[78:79] offset:128
	s_add_i32 m0, s62, 0x1f80
	s_mov_b64 s[98:99], s[78:79]
	s_add_u32 s78, s78, 0x160080
	s_addc_u32 s79, s79, 0
	s_add_i32 s62, s63, s35
	global_load_lds_dwordx4 v134, s[98:99] offset:128
	s_mov_b32 m0, s62
	s_nop 0
	global_load_lds_dwordx4 v130, s[78:79]
	s_add_i32 m0, s62, 0x2000
	s_nop 0
	global_load_lds_dwordx4 v134, s[78:79]
	s_add_i32 m0, s83, 0xffffff80
	s_nop 0
	global_load_lds_dwordx4 v128, s[100:101] offset:128
	s_add_i32 m0, s84, 0xffffff80
	s_nop 0
	global_load_lds_dwordx4 v132, s[100:101] offset:128
	s_waitcnt vmcnt(8)
	s_waitcnt lgkmcnt(0)
	s_setprio 1
	s_barrier
	v_mfma_f32_16x16x32_bf16 v[60:63], v[144:147], v[188:191], v[60:63]
	v_mfma_f32_16x16x32_bf16 v[60:63], v[160:163], v[192:195], v[60:63]
	v_mfma_f32_16x16x32_bf16 v[44:47], v[144:147], v[196:199], v[44:47]
	v_mfma_f32_16x16x32_bf16 v[44:47], v[160:163], v[200:203], v[44:47]
	v_mfma_f32_16x16x32_bf16 v[28:31], v[144:147], v[204:207], v[28:31]
	v_mfma_f32_16x16x32_bf16 v[28:31], v[160:163], v[208:211], v[28:31]
	v_mfma_f32_16x16x32_bf16 v[12:15], v[144:147], v[212:215], v[12:15]
	v_mfma_f32_16x16x32_bf16 v[12:15], v[160:163], v[216:219], v[12:15]
	v_mfma_f32_16x16x32_bf16 v[8:11], v[164:167], v[212:215], v[8:11]
	v_mfma_f32_16x16x32_bf16 v[8:11], v[168:171], v[216:219], v[8:11]
	v_mfma_f32_16x16x32_bf16 v[24:27], v[164:167], v[204:207], v[24:27]
	v_mfma_f32_16x16x32_bf16 v[24:27], v[168:171], v[208:211], v[24:27]
	v_mfma_f32_16x16x32_bf16 v[40:43], v[164:167], v[196:199], v[40:43]
	v_mfma_f32_16x16x32_bf16 v[40:43], v[168:171], v[200:203], v[40:43]
	v_mfma_f32_16x16x32_bf16 v[56:59], v[164:167], v[188:191], v[56:59]
	v_mfma_f32_16x16x32_bf16 v[56:59], v[168:171], v[192:195], v[56:59]
	v_mfma_f32_16x16x32_bf16 v[52:55], v[172:175], v[188:191], v[52:55]
	v_mfma_f32_16x16x32_bf16 v[52:55], v[176:179], v[192:195], v[52:55]
	v_mfma_f32_16x16x32_bf16 v[36:39], v[172:175], v[196:199], v[36:39]
	v_mfma_f32_16x16x32_bf16 v[36:39], v[176:179], v[200:203], v[36:39]
	v_mfma_f32_16x16x32_bf16 v[20:23], v[172:175], v[204:207], v[20:23]
	v_mfma_f32_16x16x32_bf16 v[20:23], v[176:179], v[208:211], v[20:23]
	v_mfma_f32_16x16x32_bf16 v[4:7], v[172:175], v[212:215], v[4:7]
	v_mfma_f32_16x16x32_bf16 v[4:7], v[176:179], v[216:219], v[4:7]
	v_mfma_f32_16x16x32_bf16 v[0:3], v[180:183], v[212:215], v[0:3]
	v_mfma_f32_16x16x32_bf16 v[0:3], v[184:187], v[216:219], v[0:3]
	v_mfma_f32_16x16x32_bf16 v[16:19], v[180:183], v[204:207], v[16:19]
	v_mfma_f32_16x16x32_bf16 v[16:19], v[184:187], v[208:211], v[16:19]
	s_setprio 2
	s_barrier
	v_mfma_f32_16x16x32_bf16 v[32:35], v[180:183], v[196:199], v[32:35]
	v_mfma_f32_16x16x32_bf16 v[32:35], v[184:187], v[200:203], v[32:35]
	v_mfma_f32_16x16x32_bf16 v[48:51], v[180:183], v[188:191], v[48:51]
	v_mfma_f32_16x16x32_bf16 v[48:51], v[184:187], v[192:195], v[48:51]
	s_setprio 0
	s_add_i32 s92, s92, 2
	s_add_u32 s76, s76, 0x100
	s_addc_u32 s77, s77, 0
	s_add_u32 s50, s50, 0x100
	s_addc_u32 s91, s91, 0
	s_cmpk_gt_u32 s92, 0x55
	s_cbranch_scc0 .LBB0_179
	s_and_b64 vcc, exec, s[58:59]
	s_cbranch_vccz .LBB0_182
	s_barrier

; #define PG8_STAGE(bufoff, gbase, voff) do { _Pragma("unroll") for (int _i = 0; _i < 2; ++_i) \
;         __builtin_amdgcn_global_load_lds((const unsigned*)((const char*)(gbase) + (voff)[_i]), (PG8_LAS unsigned*)(lds + (bufoff) + ldsw + _i * 8192), 16, 0, 0); } while (0)
; #define PG8_LDA(dst, b, h) do { _Pragma("unroll") for (int m = 0; m < 4; ++m) _Pragma("unroll") for (int k = 0; k < 2; ++k) dst[m][k] = *(const PG8_LAS bf16x8*)(lds + PG8_SA(b, h) + aoff + m * 2048 + k * 1024); } while (0)
; #define PG8_LDB(dst, b, h) do { _Pragma("unroll") for (int n = 0; n < 2; ++n) _Pragma("unroll") for (int k = 0; k < 2; ++k) dst[n][k] = *(const PG8_LAS bf16x8*)(lds + PG8_SB(b, h) + boff + n * 2048 + k * 1024); } while (0)
; #define PG8_MMA(ai, bj, At, Bt) do { __builtin_amdgcn_s_setprio(1); _Pragma("unroll") for (int m = 0; m < 4; ++m) _Pragma("unroll") for (int n = 0; n < 2; ++n) _Pragma("unroll") for (int k = 0; k < 2; ++k) \
;         acc[ai][bj][m][n] = __builtin_amdgcn_mfma_f32_16x16x32_bf16(Bt[n][k], At[m][k], acc[ai][bj][m][n], 0, 0, 0); __builtin_amdgcn_s_setprio(0); } while (0)
; #define PG8_WAIT_V(n) asm volatile("s_waitcnt vmcnt(" #n ")" ::: "memory")
; #define PG8_WAIT_L(n) asm volatile("s_waitcnt lgkmcnt(" #n ")" ::: "memory")
; template <class Epi, class Sched, bool ALIGN_EPI = false, bool SP2 = false>
; __device__ __forceinline__ void gemm_phase(PG8_LAS unsigned char* lds, const Gemm g, const Sched& S, const Epi& E) {
;     ...
;             const bool last = (t == nt - 2);
;             const char* a1 = cA + (size_t)(t + 1) * kstep;
;             const char* a2 = last ? nA : cA + (size_t)(t + 2) * kstep; const char* b2 = last ? nB : cB + (size_t)(t + 2) * kstep;
;             const char* a3 = a2 + kstep; const char* b3 = b2 + kstep;
;             if (last && has_next) S.a_ready(nxt);
;             if constexpr (SP2) {
;             PG8_LDB(B0, 0, 0); PG8_LDB(B1, 0, 1); PG8_SCHED; PG8_LDA(At, 0, 0); PG8_STAGE(PG8_SA(1, 1), a1 + hstep, voffA);
;             PG8_WAIT_V(8); PG8_WAIT_L(0); PG8_BAR; PG8_MMA(0, 0, At, B0); PG8_MMA(0, 1, At, B1); PG8_BAR; PG8_SCHED;
;             PG8_LDA(At, 0, 1); PG8_STAGE(PG8_SB(0, 0), b2, voffB); PG8_STAGE(PG8_SB(0, 1), b2 + hstep, voffB); PG8_STAGE(PG8_SA(0, 0), a2, voffA);
;             PG8_WAIT_V(8); PG8_WAIT_L(0); PG8_BAR; PG8_MMA(1, 0, At, B0); PG8_MMA(1, 1, At, B1); PG8_BAR; PG8_SCHED;
.LBB0_326:
	ds_read_b128 v[178:181], v176
	ds_read_b128 v[182:185], v176 offset:1024
	ds_read_b128 v[186:189], v176 offset:2048
	ds_read_b128 v[190:193], v176 offset:3072
	ds_read_b128 v[194:197], v177
	ds_read_b128 v[198:201], v177 offset:1024
	ds_read_b128 v[202:205], v177 offset:2048
	ds_read_b128 v[206:209], v177 offset:3072
	s_add_u32 s62, s76, 0xfff80080
	s_addc_u32 s63, s77, -1
	s_cmp_eq_u32 s75, 28
	s_cselect_b32 s81, s10, s63
	s_cselect_b32 s80, s11, s62
	s_cselect_b32 s79, s51, s67
	s_cselect_b32 s78, s55, s57
	s_add_i32 m0, s64, 0xc000
	ds_read_b128 v[210:213], v145
	ds_read_b128 v[214:217], v145 offset:1024
	ds_read_b128 v[218:221], v145 offset:2048
	ds_read_b128 v[222:225], v145 offset:3072
	ds_read_b128 v[226:229], v145 offset:4096
	ds_read_b128 v[230:233], v145 offset:5120
	ds_read_b128 v[234:237], v145 offset:6144
	ds_read_b128 v[238:241], v145 offset:7168
	global_load_lds_dwordx4 v146, s[76:77]
	s_add_i32 m0, s64, 0xe000
	s_nop 0
	global_load_lds_dwordx4 v152, s[76:77]
	s_waitcnt vmcnt(8)
	s_waitcnt lgkmcnt(0)
	s_setprio 1
	s_barrier
	v_mfma_f32_16x16x32_bf16 v[124:127], v[178:181], v[210:213], v[124:127]
	v_mfma_f32_16x16x32_bf16 v[124:127], v[182:185], v[214:217], v[124:127]
	v_mfma_f32_16x16x32_bf16 v[116:119], v[178:181], v[218:221], v[116:119]
	v_mfma_f32_16x16x32_bf16 v[116:119], v[182:185], v[222:225], v[116:119]
	v_mfma_f32_16x16x32_bf16 v[108:111], v[178:181], v[226:229], v[108:111]
	v_mfma_f32_16x16x32_bf16 v[108:111], v[182:185], v[230:233], v[108:111]
	v_mfma_f32_16x16x32_bf16 v[100:103], v[178:181], v[234:237], v[100:103]
	v_mfma_f32_16x16x32_bf16 v[100:103], v[182:185], v[238:241], v[100:103]
	v_mfma_f32_16x16x32_bf16 v[96:99], v[186:189], v[234:237], v[96:99]
	v_mfma_f32_16x16x32_bf16 v[96:99], v[190:193], v[238:241], v[96:99]
	v_mfma_f32_16x16x32_bf16 v[104:107], v[186:189], v[226:229], v[104:107]
	v_mfma_f32_16x16x32_bf16 v[104:107], v[190:193], v[230:233], v[104:107]
	v_mfma_f32_16x16x32_bf16 v[112:115], v[186:189], v[218:221], v[112:115]
	v_mfma_f32_16x16x32_bf16 v[112:115], v[190:193], v[222:225], v[112:115]
	v_mfma_f32_16x16x32_bf16 v[120:123], v[186:189], v[210:213], v[120:123]
	v_mfma_f32_16x16x32_bf16 v[120:123], v[190:193], v[214:217], v[120:123]
	v_mfma_f32_16x16x32_bf16 v[68:71], v[194:197], v[210:213], v[68:71]
	v_mfma_f32_16x16x32_bf16 v[68:71], v[198:201], v[214:217], v[68:71]
	v_mfma_f32_16x16x32_bf16 v[52:55], v[194:197], v[218:221], v[52:55]
	v_mfma_f32_16x16x32_bf16 v[52:55], v[198:201], v[222:225], v[52:55]
	v_mfma_f32_16x16x32_bf16 v[44:47], v[194:197], v[226:229], v[44:47]
	v_mfma_f32_16x16x32_bf16 v[44:47], v[198:201], v[230:233], v[44:47]
	v_mfma_f32_16x16x32_bf16 v[36:39], v[194:197], v[234:237], v[36:39]
	v_mfma_f32_16x16x32_bf16 v[36:39], v[198:201], v[238:241], v[36:39]
	v_mfma_f32_16x16x32_bf16 v[32:35], v[202:205], v[234:237], v[32:35]
	v_mfma_f32_16x16x32_bf16 v[32:35], v[206:209], v[238:241], v[32:35]
	v_mfma_f32_16x16x32_bf16 v[40:43], v[202:205], v[226:229], v[40:43]
	v_mfma_f32_16x16x32_bf16 v[40:43], v[206:209], v[230:233], v[40:43]
	s_setprio 2
	s_barrier
	v_mfma_f32_16x16x32_bf16 v[48:51], v[202:205], v[218:221], v[48:51]
	v_mfma_f32_16x16x32_bf16 v[48:51], v[206:209], v[222:225], v[48:51]
	v_mfma_f32_16x16x32_bf16 v[64:67], v[202:205], v[210:213], v[64:67]
	v_mfma_f32_16x16x32_bf16 v[64:67], v[206:209], v[214:217], v[64:67]
	s_setprio 0
	s_add_i32 s62, s53, s3
	s_mov_b32 m0, s62
	ds_read_b128 v[210:213], v145 offset:16384
	ds_read_b128 v[214:217], v145 offset:17408
	ds_read_b128 v[218:221], v145 offset:18432
	ds_read_b128 v[222:225], v145 offset:19456
	ds_read_b128 v[226:229], v145 offset:20480
	ds_read_b128 v[230:233], v145 offset:21504
	ds_read_b128 v[234:237], v145 offset:22528
	ds_read_b128 v[238:241], v145 offset:23552
	global_load_lds_dwordx4 v130, s[78:79]
	s_add_i32 m0, s62, 0x2000
	s_add_u32 s82, s78, 0x80000
	s_addc_u32 s83, s79, 0
	s_add_i32 s62, s66, s3
	global_load_lds_dwordx4 v134, s[78:79]
	s_mov_b32 m0, s62
	s_nop 0
	global_load_lds_dwordx4 v130, s[82:83]
	s_add_i32 m0, s62, 0x2000
	s_nop 0
	global_load_lds_dwordx4 v134, s[82:83]
	s_mov_b32 m0, s64
	s_nop 0
	global_load_lds_dwordx4 v128, s[80:81]
	s_mov_b32 m0, s65
	s_nop 0
	global_load_lds_dwordx4 v132, s[80:81]
	s_waitcnt vmcnt(8)
	s_waitcnt lgkmcnt(0)
	s_setprio 1
	s_barrier
	v_mfma_f32_16x16x32_bf16 v[92:95], v[178:181], v[210:213], v[92:95]
	v_mfma_f32_16x16x32_bf16 v[92:95], v[182:185], v[214:217], v[92:95]
	v_mfma_f32_16x16x32_bf16 v[84:87], v[178:181], v[218:221], v[84:87]
	v_mfma_f32_16x16x32_bf16 v[84:87], v[182:185], v[222:225], v[84:87]
	v_mfma_f32_16x16x32_bf16 v[76:79], v[178:181], v[226:229], v[76:79]
	v_mfma_f32_16x16x32_bf16 v[76:79], v[182:185], v[230:233], v[76:79]
	v_mfma_f32_16x16x32_bf16 v[60:63], v[178:181], v[234:237], v[60:63]
	v_mfma_f32_16x16x32_bf16 v[60:63], v[182:185], v[238:241], v[60:63]
	v_mfma_f32_16x16x32_bf16 v[56:59], v[186:189], v[234:237], v[56:59]
	v_mfma_f32_16x16x32_bf16 v[56:59], v[190:193], v[238:241], v[56:59]
	v_mfma_f32_16x16x32_bf16 v[72:75], v[186:189], v[226:229], v[72:75]
	v_mfma_f32_16x16x32_bf16 v[72:75], v[190:193], v[230:233], v[72:75]
	v_mfma_f32_16x16x32_bf16 v[80:83], v[186:189], v[218:221], v[80:83]
	v_mfma_f32_16x16x32_bf16 v[80:83], v[190:193], v[222:225], v[80:83]
	v_mfma_f32_16x16x32_bf16 v[88:91], v[186:189], v[210:213], v[88:91]
	v_mfma_f32_16x16x32_bf16 v[88:91], v[190:193], v[214:217], v[88:91]
	v_mfma_f32_16x16x32_bf16 v[28:31], v[194:197], v[210:213], v[28:31]
	v_mfma_f32_16x16x32_bf16 v[28:31], v[198:201], v[214:217], v[28:31]
	v_mfma_f32_16x16x32_bf16 v[20:23], v[194:197], v[218:221], v[20:23]
	v_mfma_f32_16x16x32_bf16 v[20:23], v[198:201], v[222:225], v[20:23]
	v_mfma_f32_16x16x32_bf16 v[12:15], v[194:197], v[226:229], v[12:15]
	v_mfma_f32_16x16x32_bf16 v[12:15], v[198:201], v[230:233], v[12:15]
	v_mfma_f32_16x16x32_bf16 v[4:7], v[194:197], v[234:237], v[4:7]
	v_mfma_f32_16x16x32_bf16 v[4:7], v[198:201], v[238:241], v[4:7]
	v_mfma_f32_16x16x32_bf16 v[0:3], v[202:205], v[234:237], v[0:3]
	v_mfma_f32_16x16x32_bf16 v[0:3], v[206:209], v[238:241], v[0:3]
	v_mfma_f32_16x16x32_bf16 v[8:11], v[202:205], v[226:229], v[8:11]
	v_mfma_f32_16x16x32_bf16 v[8:11], v[206:209], v[230:233], v[8:11]
	s_setprio 2
	s_barrier
; #define PG8_STAGE(bufoff, gbase, voff) do { _Pragma("unroll") for (int _i = 0; _i < 2; ++_i) \
;         __builtin_amdgcn_global_load_lds((const unsigned*)((const char*)(gbase) + (voff)[_i]), (PG8_LAS unsigned*)(lds + (bufoff) + ldsw + _i * 8192), 16, 0, 0); } while (0)
; #define PG8_LDA(dst, b, h) do { _Pragma("unroll") for (int m = 0; m < 4; ++m) _Pragma("unroll") for (int k = 0; k < 2; ++k) dst[m][k] = *(const PG8_LAS bf16x8*)(lds + PG8_SA(b, h) + aoff + m * 2048 + k * 1024); } while (0)
; #define PG8_LDB(dst, b, h) do { _Pragma("unroll") for (int n = 0; n < 2; ++n) _Pragma("unroll") for (int k = 0; k < 2; ++k) dst[n][k] = *(const PG8_LAS bf16x8*)(lds + PG8_SB(b, h) + boff + n * 2048 + k * 1024); } while (0)
; #define PG8_MMA(ai, bj, At, Bt) do { __builtin_amdgcn_s_setprio(1); _Pragma("unroll") for (int m = 0; m < 4; ++m) _Pragma("unroll") for (int n = 0; n < 2; ++n) _Pragma("unroll") for (int k = 0; k < 2; ++k) \
;         acc[ai][bj][m][n] = __builtin_amdgcn_mfma_f32_16x16x32_bf16(Bt[n][k], At[m][k], acc[ai][bj][m][n], 0, 0, 0); __builtin_amdgcn_s_setprio(0); } while (0)
; #define PG8_WAIT_V(n) asm volatile("s_waitcnt vmcnt(" #n ")" ::: "memory")
; #define PG8_WAIT_L(n) asm volatile("s_waitcnt lgkmcnt(" #n ")" ::: "memory")
; #define PG8_BAR __builtin_amdgcn_s_barrier()
; #define PG8_SCHED __builtin_amdgcn_sched_barrier(0)
; template <class Epi, class Sched, bool ALIGN_EPI = false, bool SP2 = false>
; __device__ __forceinline__ void gemm_phase(PG8_LAS unsigned char* lds, const Gemm g, const Sched& S, const Epi& E) {
;     ...
;             PG8_WAIT_V(8); PG8_WAIT_L(0); PG8_BAR; PG8_MMA(1, 0, At, B0); PG8_MMA(1, 1, At, B1); PG8_BAR; PG8_SCHED;
;             PG8_LDB(B0, 1, 0); PG8_LDB(B1, 1, 1); PG8_SCHED; PG8_LDA(At, 1, 0); PG8_STAGE(PG8_SA(0, 1), a2 + hstep, voffA);
;             PG8_WAIT_V(8); PG8_WAIT_L(0); PG8_BAR; PG8_MMA(0, 0, At, B0); PG8_MMA(0, 1, At, B1); PG8_BAR; PG8_SCHED;
	v_mfma_f32_16x16x32_bf16 v[16:19], v[202:205], v[218:221], v[16:19]
	v_mfma_f32_16x16x32_bf16 v[16:19], v[206:209], v[222:225], v[16:19]
	v_mfma_f32_16x16x32_bf16 v[24:27], v[202:205], v[210:213], v[24:27]
	v_mfma_f32_16x16x32_bf16 v[24:27], v[206:209], v[214:217], v[24:27]
	s_setprio 0
	s_add_i32 s62, 0, 0x18000
	s_add_i32 s63, 0, 0x1c000
	v_add_u32_e32 v190, s62, v143
	v_add_u32_e32 v206, s63, v143
	ds_read_b128 v[178:181], v190
	ds_read_b128 v[182:185], v190 offset:1024
	ds_read_b128 v[186:189], v190 offset:2048
	ds_read_b128 v[190:193], v190 offset:3072
	ds_read_b128 v[194:197], v206
	ds_read_b128 v[198:201], v206 offset:1024
	ds_read_b128 v[202:205], v206 offset:2048
	ds_read_b128 v[206:209], v206 offset:3072
	s_mov_b64 s[100:101], s[80:81]
	s_add_u32 s80, s80, 0x80000
	s_addc_u32 s81, s81, 0
	s_mov_b32 m0, s86
	ds_read_b128 v[210:213], v145 offset:32768
	ds_read_b128 v[214:217], v145 offset:33792
	ds_read_b128 v[218:221], v145 offset:34816
	ds_read_b128 v[222:225], v145 offset:35840
	ds_read_b128 v[226:229], v145 offset:36864
	ds_read_b128 v[230:233], v145 offset:37888
	ds_read_b128 v[234:237], v145 offset:38912
	ds_read_b128 v[238:241], v145 offset:39936
	global_load_lds_dwordx4 v128, s[80:81]
	s_mov_b32 m0, s87
	s_nop 0
	global_load_lds_dwordx4 v132, s[80:81]
	s_waitcnt vmcnt(8)
	s_waitcnt lgkmcnt(0)
	s_setprio 1
	s_barrier
	v_mfma_f32_16x16x32_bf16 v[124:127], v[178:181], v[210:213], v[124:127]
	v_mfma_f32_16x16x32_bf16 v[124:127], v[182:185], v[214:217], v[124:127]
	v_mfma_f32_16x16x32_bf16 v[116:119], v[178:181], v[218:221], v[116:119]
	v_mfma_f32_16x16x32_bf16 v[116:119], v[182:185], v[222:225], v[116:119]
	v_mfma_f32_16x16x32_bf16 v[108:111], v[178:181], v[226:229], v[108:111]
	v_mfma_f32_16x16x32_bf16 v[108:111], v[182:185], v[230:233], v[108:111]
	v_mfma_f32_16x16x32_bf16 v[100:103], v[178:181], v[234:237], v[100:103]
	v_mfma_f32_16x16x32_bf16 v[100:103], v[182:185], v[238:241], v[100:103]
	v_mfma_f32_16x16x32_bf16 v[96:99], v[186:189], v[234:237], v[96:99]
	v_mfma_f32_16x16x32_bf16 v[96:99], v[190:193], v[238:241], v[96:99]
	v_mfma_f32_16x16x32_bf16 v[104:107], v[186:189], v[226:229], v[104:107]
	v_mfma_f32_16x16x32_bf16 v[104:107], v[190:193], v[230:233], v[104:107]
	v_mfma_f32_16x16x32_bf16 v[112:115], v[186:189], v[218:221], v[112:115]
	v_mfma_f32_16x16x32_bf16 v[112:115], v[190:193], v[222:225], v[112:115]
	v_mfma_f32_16x16x32_bf16 v[120:123], v[186:189], v[210:213], v[120:123]
	v_mfma_f32_16x16x32_bf16 v[120:123], v[190:193], v[214:217], v[120:123]
	v_mfma_f32_16x16x32_bf16 v[68:71], v[194:197], v[210:213], v[68:71]
	v_mfma_f32_16x16x32_bf16 v[68:71], v[198:201], v[214:217], v[68:71]
	v_mfma_f32_16x16x32_bf16 v[52:55], v[194:197], v[218:221], v[52:55]
	v_mfma_f32_16x16x32_bf16 v[52:55], v[198:201], v[222:225], v[52:55]
	v_mfma_f32_16x16x32_bf16 v[44:47], v[194:197], v[226:229], v[44:47]
	v_mfma_f32_16x16x32_bf16 v[44:47], v[198:201], v[230:233], v[44:47]
	v_mfma_f32_16x16x32_bf16 v[36:39], v[194:197], v[234:237], v[36:39]
	v_mfma_f32_16x16x32_bf16 v[36:39], v[198:201], v[238:241], v[36:39]
	v_mfma_f32_16x16x32_bf16 v[32:35], v[202:205], v[234:237], v[32:35]
	v_mfma_f32_16x16x32_bf16 v[32:35], v[206:209], v[238:241], v[32:35]
	v_mfma_f32_16x16x32_bf16 v[40:43], v[202:205], v[226:229], v[40:43]
	v_mfma_f32_16x16x32_bf16 v[40:43], v[206:209], v[230:233], v[40:43]
	s_setprio 2
	s_barrier
; #define PG8_STAGE(bufoff, gbase, voff) do { _Pragma("unroll") for (int _i = 0; _i < 2; ++_i) \
;         __builtin_amdgcn_global_load_lds((const unsigned*)((const char*)(gbase) + (voff)[_i]), (PG8_LAS unsigned*)(lds + (bufoff) + ldsw + _i * 8192), 16, 0, 0); } while (0)
; #define PG8_LDA(dst, b, h) do { _Pragma("unroll") for (int m = 0; m < 4; ++m) _Pragma("unroll") for (int k = 0; k < 2; ++k) dst[m][k] = *(const PG8_LAS bf16x8*)(lds + PG8_SA(b, h) + aoff + m * 2048 + k * 1024); } while (0)
; #define PG8_MMA(ai, bj, At, Bt) do { __builtin_amdgcn_s_setprio(1); _Pragma("unroll") for (int m = 0; m < 4; ++m) _Pragma("unroll") for (int n = 0; n < 2; ++n) _Pragma("unroll") for (int k = 0; k < 2; ++k) \
;         acc[ai][bj][m][n] = __builtin_amdgcn_mfma_f32_16x16x32_bf16(Bt[n][k], At[m][k], acc[ai][bj][m][n], 0, 0, 0); __builtin_amdgcn_s_setprio(0); } while (0)
; #define PG8_WAIT_V(n) asm volatile("s_waitcnt vmcnt(" #n ")" ::: "memory")
; #define PG8_WAIT_L(n) asm volatile("s_waitcnt lgkmcnt(" #n ")" ::: "memory")
; #define PG8_BAR __builtin_amdgcn_s_barrier()
; #define PG8_SCHED __builtin_amdgcn_sched_barrier(0)
; template <class Epi, class Sched, bool ALIGN_EPI = false, bool SP2 = false>
; __device__ __forceinline__ void gemm_phase(PG8_LAS unsigned char* lds, const Gemm g, const Sched& S, const Epi& E) {
;     ...
;             PG8_WAIT_V(8); PG8_WAIT_L(0); PG8_BAR; PG8_MMA(0, 0, At, B0); PG8_MMA(0, 1, At, B1); PG8_BAR; PG8_SCHED;
;             PG8_LDA(At, 1, 1); PG8_STAGE(PG8_SB(1, 0), b3, voffB); PG8_STAGE(PG8_SB(1, 1), b3 + hstep, voffB); PG8_STAGE(PG8_SA(1, 0), a3, voffA);
;             PG8_WAIT_V(8); PG8_WAIT_L(0); PG8_BAR; PG8_MMA(1, 0, At, B0); PG8_MMA(1, 1, At, B1); PG8_BAR; PG8_SCHED;
;     ...
;         if constexpr (ALIGN_EPI) { if (wr == 0) PG8_BAR; }
	v_mfma_f32_16x16x32_bf16 v[48:51], v[202:205], v[218:221], v[48:51]
	v_mfma_f32_16x16x32_bf16 v[48:51], v[206:209], v[222:225], v[48:51]
	v_mfma_f32_16x16x32_bf16 v[64:67], v[202:205], v[210:213], v[64:67]
	v_mfma_f32_16x16x32_bf16 v[64:67], v[206:209], v[214:217], v[64:67]
	s_setprio 0
	s_add_i32 s62, s62, s3
	s_add_i32 m0, s62, 0xffffff80
	ds_read_b128 v[210:213], v145 offset:49152
	ds_read_b128 v[214:217], v145 offset:50176
	ds_read_b128 v[218:221], v145 offset:51200
	ds_read_b128 v[222:225], v145 offset:52224
	ds_read_b128 v[226:229], v145 offset:53248
	ds_read_b128 v[230:233], v145 offset:54272
	ds_read_b128 v[234:237], v145 offset:55296
	ds_read_b128 v[238:241], v145 offset:56320
	global_load_lds_dwordx4 v130, s[78:79] offset:128
	s_add_i32 m0, s62, 0x1f80
	s_mov_b64 s[98:99], s[78:79]
	s_add_u32 s78, s78, 0x80080
	s_addc_u32 s79, s79, 0
	s_add_i32 s62, s63, s3
	global_load_lds_dwordx4 v134, s[98:99] offset:128
	s_mov_b32 m0, s62
	s_nop 0
	global_load_lds_dwordx4 v130, s[78:79]
	s_add_i32 m0, s62, 0x2000
	s_nop 0
	global_load_lds_dwordx4 v134, s[78:79]
	s_add_i32 m0, s89, 0xffffff80
	s_nop 0
	global_load_lds_dwordx4 v128, s[100:101] offset:128
	s_add_i32 m0, s90, 0xffffff80
	s_nop 0
	global_load_lds_dwordx4 v132, s[100:101] offset:128
	s_waitcnt vmcnt(8)
	s_waitcnt lgkmcnt(0)
	s_setprio 1
	s_barrier
	v_mfma_f32_16x16x32_bf16 v[92:95], v[178:181], v[210:213], v[92:95]
	v_mfma_f32_16x16x32_bf16 v[92:95], v[182:185], v[214:217], v[92:95]
	v_mfma_f32_16x16x32_bf16 v[84:87], v[178:181], v[218:221], v[84:87]
	v_mfma_f32_16x16x32_bf16 v[84:87], v[182:185], v[222:225], v[84:87]
	v_mfma_f32_16x16x32_bf16 v[76:79], v[178:181], v[226:229], v[76:79]
	v_mfma_f32_16x16x32_bf16 v[76:79], v[182:185], v[230:233], v[76:79]
	v_mfma_f32_16x16x32_bf16 v[60:63], v[178:181], v[234:237], v[60:63]
	v_mfma_f32_16x16x32_bf16 v[60:63], v[182:185], v[238:241], v[60:63]
	v_mfma_f32_16x16x32_bf16 v[56:59], v[186:189], v[234:237], v[56:59]
	v_mfma_f32_16x16x32_bf16 v[56:59], v[190:193], v[238:241], v[56:59]
	v_mfma_f32_16x16x32_bf16 v[72:75], v[186:189], v[226:229], v[72:75]
	v_mfma_f32_16x16x32_bf16 v[72:75], v[190:193], v[230:233], v[72:75]
	v_mfma_f32_16x16x32_bf16 v[80:83], v[186:189], v[218:221], v[80:83]
	v_mfma_f32_16x16x32_bf16 v[80:83], v[190:193], v[222:225], v[80:83]
	v_mfma_f32_16x16x32_bf16 v[88:91], v[186:189], v[210:213], v[88:91]
	v_mfma_f32_16x16x32_bf16 v[88:91], v[190:193], v[214:217], v[88:91]
	v_mfma_f32_16x16x32_bf16 v[28:31], v[194:197], v[210:213], v[28:31]
	v_mfma_f32_16x16x32_bf16 v[28:31], v[198:201], v[214:217], v[28:31]
	v_mfma_f32_16x16x32_bf16 v[20:23], v[194:197], v[218:221], v[20:23]
	v_mfma_f32_16x16x32_bf16 v[20:23], v[198:201], v[222:225], v[20:23]
	v_mfma_f32_16x16x32_bf16 v[12:15], v[194:197], v[226:229], v[12:15]
	v_mfma_f32_16x16x32_bf16 v[12:15], v[198:201], v[230:233], v[12:15]
	v_mfma_f32_16x16x32_bf16 v[4:7], v[194:197], v[234:237], v[4:7]
	v_mfma_f32_16x16x32_bf16 v[4:7], v[198:201], v[238:241], v[4:7]
	v_mfma_f32_16x16x32_bf16 v[0:3], v[202:205], v[234:237], v[0:3]
	v_mfma_f32_16x16x32_bf16 v[0:3], v[206:209], v[238:241], v[0:3]
	v_mfma_f32_16x16x32_bf16 v[8:11], v[202:205], v[226:229], v[8:11]
	v_mfma_f32_16x16x32_bf16 v[8:11], v[206:209], v[230:233], v[8:11]
	s_setprio 2
	s_barrier
	v_mfma_f32_16x16x32_bf16 v[16:19], v[202:205], v[218:221], v[16:19]
	v_mfma_f32_16x16x32_bf16 v[16:19], v[206:209], v[222:225], v[16:19]
	v_mfma_f32_16x16x32_bf16 v[24:27], v[202:205], v[210:213], v[24:27]
	v_mfma_f32_16x16x32_bf16 v[24:27], v[206:209], v[214:217], v[24:27]
	s_setprio 0
	s_add_i32 s75, s75, 2
	s_add_u32 s76, s76, 0x100
	s_addc_u32 s77, s77, 0
	s_add_u32 s57, s57, 0x100
	s_addc_u32 s67, s67, 0
	s_cmp_gt_u32 s75, 29
	s_cbranch_scc0 .LBB0_326
	s_and_b64 vcc, exec, s[20:21]
	s_cbranch_vccz .LBB0_329
	s_barrier

; #define PG8_STAGE(bufoff, gbase, voff) do { _Pragma("unroll") for (int _i = 0; _i < 2; ++_i) \
;         __builtin_amdgcn_global_load_lds((const unsigned*)((const char*)(gbase) + (voff)[_i]), (PG8_LAS unsigned*)(lds + (bufoff) + ldsw + _i * 8192), 16, 0, 0); } while (0)
; #define PG8_LDA(dst, b, h) do { _Pragma("unroll") for (int m = 0; m < 4; ++m) _Pragma("unroll") for (int k = 0; k < 2; ++k) dst[m][k] = *(const PG8_LAS bf16x8*)(lds + PG8_SA(b, h) + aoff + m * 2048 + k * 1024); } while (0)
; #define PG8_LDB(dst, b, h) do { _Pragma("unroll") for (int n = 0; n < 2; ++n) _Pragma("unroll") for (int k = 0; k < 2; ++k) dst[n][k] = *(const PG8_LAS bf16x8*)(lds + PG8_SB(b, h) + boff + n * 2048 + k * 1024); } while (0)
; #define PG8_MMA(ai, bj, At, Bt) do { __builtin_amdgcn_s_setprio(1); _Pragma("unroll") for (int m = 0; m < 4; ++m) _Pragma("unroll") for (int n = 0; n < 2; ++n) _Pragma("unroll") for (int k = 0; k < 2; ++k) \
;         acc[ai][bj][m][n] = __builtin_amdgcn_mfma_f32_16x16x32_bf16(Bt[n][k], At[m][k], acc[ai][bj][m][n], 0, 0, 0); __builtin_amdgcn_s_setprio(0); } while (0)
; #define PG8_WAIT_V(n) asm volatile("s_waitcnt vmcnt(" #n ")" ::: "memory")
; #define PG8_WAIT_L(n) asm volatile("s_waitcnt lgkmcnt(" #n ")" ::: "memory")
; template <class Epi, class Sched, bool ALIGN_EPI = false, bool SP2 = false>
; __device__ __forceinline__ void gemm_phase(PG8_LAS unsigned char* lds, const Gemm g, const Sched& S, const Epi& E) {
;     ...
;             const bool last = (t == nt - 2);
;             const char* a1 = cA + (size_t)(t + 1) * kstep;
;             const char* a2 = last ? nA : cA + (size_t)(t + 2) * kstep; const char* b2 = last ? nB : cB + (size_t)(t + 2) * kstep;
;             const char* a3 = a2 + kstep; const char* b3 = b2 + kstep;
;             if (last && has_next) S.a_ready(nxt);
;             if constexpr (SP2) {
;             PG8_LDB(B0, 0, 0); PG8_LDB(B1, 0, 1); PG8_SCHED; PG8_LDA(At, 0, 0); PG8_STAGE(PG8_SA(1, 1), a1 + hstep, voffA);
;             PG8_WAIT_V(8); PG8_WAIT_L(0); PG8_BAR; PG8_MMA(0, 0, At, B0); PG8_MMA(0, 1, At, B1); PG8_BAR; PG8_SCHED;
;             PG8_LDA(At, 0, 1); PG8_STAGE(PG8_SB(0, 0), b2, voffB); PG8_STAGE(PG8_SB(0, 1), b2 + hstep, voffB); PG8_STAGE(PG8_SA(0, 0), a2, voffA);
;             PG8_WAIT_V(8); PG8_WAIT_L(0); PG8_BAR; PG8_MMA(1, 0, At, B0); PG8_MMA(1, 1, At, B1); PG8_BAR; PG8_SCHED;
.LBB0_557:
	ds_read_b128 v[144:147], v155
	ds_read_b128 v[160:163], v155 offset:1024
	ds_read_b128 v[164:167], v155 offset:2048
	ds_read_b128 v[168:171], v155 offset:3072
	ds_read_b128 v[172:175], v156
	ds_read_b128 v[176:179], v156 offset:1024
	ds_read_b128 v[180:183], v156 offset:2048
	ds_read_b128 v[184:187], v156 offset:3072
	s_add_u32 s54, s50, 0xfff80080
	s_addc_u32 s55, s51, -1
	s_cmp_eq_u32 s73, 28
	s_cselect_b32 s57, s10, s55
	s_cselect_b32 s56, s11, s54
	s_cselect_b32 s55, s41, s72
	s_cselect_b32 s54, s43, s49
	s_add_i32 m0, s33, 0xc000
	ds_read_b128 v[188:191], v157
	ds_read_b128 v[192:195], v157 offset:1024
	ds_read_b128 v[196:199], v157 offset:2048
	ds_read_b128 v[200:203], v157 offset:3072
	ds_read_b128 v[204:207], v157 offset:4096
	ds_read_b128 v[208:211], v157 offset:5120
	ds_read_b128 v[212:215], v157 offset:6144
	ds_read_b128 v[216:219], v157 offset:7168
	global_load_lds_dwordx4 v136, s[50:51]
	s_add_i32 m0, s33, 0xe000
	s_nop 0
	global_load_lds_dwordx4 v138, s[50:51]
	s_waitcnt vmcnt(8)
	s_waitcnt lgkmcnt(0)
	s_setprio 1
	s_barrier
	v_mfma_f32_16x16x32_bf16 v[124:127], v[144:147], v[188:191], v[124:127]
	v_mfma_f32_16x16x32_bf16 v[124:127], v[160:163], v[192:195], v[124:127]
	v_mfma_f32_16x16x32_bf16 v[108:111], v[144:147], v[196:199], v[108:111]
	v_mfma_f32_16x16x32_bf16 v[108:111], v[160:163], v[200:203], v[108:111]
	v_mfma_f32_16x16x32_bf16 v[92:95], v[144:147], v[204:207], v[92:95]
	v_mfma_f32_16x16x32_bf16 v[92:95], v[160:163], v[208:211], v[92:95]
	v_mfma_f32_16x16x32_bf16 v[76:79], v[144:147], v[212:215], v[76:79]
	v_mfma_f32_16x16x32_bf16 v[76:79], v[160:163], v[216:219], v[76:79]
	v_mfma_f32_16x16x32_bf16 v[72:75], v[164:167], v[212:215], v[72:75]
	v_mfma_f32_16x16x32_bf16 v[72:75], v[168:171], v[216:219], v[72:75]
	v_mfma_f32_16x16x32_bf16 v[88:91], v[164:167], v[204:207], v[88:91]
	v_mfma_f32_16x16x32_bf16 v[88:91], v[168:171], v[208:211], v[88:91]
	v_mfma_f32_16x16x32_bf16 v[104:107], v[164:167], v[196:199], v[104:107]
	v_mfma_f32_16x16x32_bf16 v[104:107], v[168:171], v[200:203], v[104:107]
	v_mfma_f32_16x16x32_bf16 v[120:123], v[164:167], v[188:191], v[120:123]
	v_mfma_f32_16x16x32_bf16 v[120:123], v[168:171], v[192:195], v[120:123]
	v_mfma_f32_16x16x32_bf16 v[116:119], v[172:175], v[188:191], v[116:119]
	v_mfma_f32_16x16x32_bf16 v[116:119], v[176:179], v[192:195], v[116:119]
	v_mfma_f32_16x16x32_bf16 v[100:103], v[172:175], v[196:199], v[100:103]
	v_mfma_f32_16x16x32_bf16 v[100:103], v[176:179], v[200:203], v[100:103]
	v_mfma_f32_16x16x32_bf16 v[84:87], v[172:175], v[204:207], v[84:87]
	v_mfma_f32_16x16x32_bf16 v[84:87], v[176:179], v[208:211], v[84:87]
	v_mfma_f32_16x16x32_bf16 v[68:71], v[172:175], v[212:215], v[68:71]
	v_mfma_f32_16x16x32_bf16 v[68:71], v[176:179], v[216:219], v[68:71]
	v_mfma_f32_16x16x32_bf16 v[64:67], v[180:183], v[212:215], v[64:67]
	v_mfma_f32_16x16x32_bf16 v[64:67], v[184:187], v[216:219], v[64:67]
	v_mfma_f32_16x16x32_bf16 v[80:83], v[180:183], v[204:207], v[80:83]
	v_mfma_f32_16x16x32_bf16 v[80:83], v[184:187], v[208:211], v[80:83]
	s_setprio 2
	s_barrier
	v_mfma_f32_16x16x32_bf16 v[96:99], v[180:183], v[196:199], v[96:99]
	v_mfma_f32_16x16x32_bf16 v[96:99], v[184:187], v[200:203], v[96:99]
	v_mfma_f32_16x16x32_bf16 v[112:115], v[180:183], v[188:191], v[112:115]
	v_mfma_f32_16x16x32_bf16 v[112:115], v[184:187], v[192:195], v[112:115]
	s_setprio 0
	s_add_i32 s62, s67, s3
	s_mov_b32 m0, s62
	ds_read_b128 v[188:191], v157 offset:16384
	ds_read_b128 v[192:195], v157 offset:17408
	ds_read_b128 v[196:199], v157 offset:18432
	ds_read_b128 v[200:203], v157 offset:19456
	ds_read_b128 v[204:207], v157 offset:20480
	ds_read_b128 v[208:211], v157 offset:21504
	ds_read_b128 v[212:215], v157 offset:22528
	ds_read_b128 v[216:219], v157 offset:23552
	global_load_lds_dwordx4 v130, s[54:55]
	s_add_i32 m0, s62, 0x2000
	s_add_u32 s62, s54, 0x80000
	s_addc_u32 s63, s55, 0
	s_add_i32 s74, s70, s3
	global_load_lds_dwordx4 v134, s[54:55]
	s_mov_b32 m0, s74
	s_nop 0
	global_load_lds_dwordx4 v130, s[62:63]
	s_add_i32 m0, s74, 0x2000
	s_nop 0
	global_load_lds_dwordx4 v134, s[62:63]
	s_mov_b32 m0, s33
	s_nop 0
	global_load_lds_dwordx4 v128, s[56:57]
	s_mov_b32 m0, s35
	s_nop 0
	global_load_lds_dwordx4 v132, s[56:57]
	s_waitcnt vmcnt(8)
	s_waitcnt lgkmcnt(0)
	s_setprio 1
	s_barrier
	v_mfma_f32_16x16x32_bf16 v[60:63], v[144:147], v[188:191], v[60:63]
	v_mfma_f32_16x16x32_bf16 v[60:63], v[160:163], v[192:195], v[60:63]
	v_mfma_f32_16x16x32_bf16 v[44:47], v[144:147], v[196:199], v[44:47]
	v_mfma_f32_16x16x32_bf16 v[44:47], v[160:163], v[200:203], v[44:47]
	v_mfma_f32_16x16x32_bf16 v[28:31], v[144:147], v[204:207], v[28:31]
	v_mfma_f32_16x16x32_bf16 v[28:31], v[160:163], v[208:211], v[28:31]
	v_mfma_f32_16x16x32_bf16 v[12:15], v[144:147], v[212:215], v[12:15]
	v_mfma_f32_16x16x32_bf16 v[12:15], v[160:163], v[216:219], v[12:15]
	v_mfma_f32_16x16x32_bf16 v[8:11], v[164:167], v[212:215], v[8:11]
	v_mfma_f32_16x16x32_bf16 v[8:11], v[168:171], v[216:219], v[8:11]
	v_mfma_f32_16x16x32_bf16 v[24:27], v[164:167], v[204:207], v[24:27]
	v_mfma_f32_16x16x32_bf16 v[24:27], v[168:171], v[208:211], v[24:27]
	v_mfma_f32_16x16x32_bf16 v[40:43], v[164:167], v[196:199], v[40:43]
	v_mfma_f32_16x16x32_bf16 v[40:43], v[168:171], v[200:203], v[40:43]
	v_mfma_f32_16x16x32_bf16 v[56:59], v[164:167], v[188:191], v[56:59]
	v_mfma_f32_16x16x32_bf16 v[56:59], v[168:171], v[192:195], v[56:59]
	v_mfma_f32_16x16x32_bf16 v[52:55], v[172:175], v[188:191], v[52:55]
	v_mfma_f32_16x16x32_bf16 v[52:55], v[176:179], v[192:195], v[52:55]
	v_mfma_f32_16x16x32_bf16 v[36:39], v[172:175], v[196:199], v[36:39]
	v_mfma_f32_16x16x32_bf16 v[36:39], v[176:179], v[200:203], v[36:39]
	v_mfma_f32_16x16x32_bf16 v[20:23], v[172:175], v[204:207], v[20:23]
	v_mfma_f32_16x16x32_bf16 v[20:23], v[176:179], v[208:211], v[20:23]
	v_mfma_f32_16x16x32_bf16 v[4:7], v[172:175], v[212:215], v[4:7]
	v_mfma_f32_16x16x32_bf16 v[4:7], v[176:179], v[216:219], v[4:7]
	v_mfma_f32_16x16x32_bf16 v[0:3], v[180:183], v[212:215], v[0:3]
	v_mfma_f32_16x16x32_bf16 v[0:3], v[184:187], v[216:219], v[0:3]
	v_mfma_f32_16x16x32_bf16 v[16:19], v[180:183], v[204:207], v[16:19]
	v_mfma_f32_16x16x32_bf16 v[16:19], v[184:187], v[208:211], v[16:19]
	s_setprio 2
	s_barrier
; #define PG8_STAGE(bufoff, gbase, voff) do { _Pragma("unroll") for (int _i = 0; _i < 2; ++_i) \
;         __builtin_amdgcn_global_load_lds((const unsigned*)((const char*)(gbase) + (voff)[_i]), (PG8_LAS unsigned*)(lds + (bufoff) + ldsw + _i * 8192), 16, 0, 0); } while (0)
; #define PG8_LDA(dst, b, h) do { _Pragma("unroll") for (int m = 0; m < 4; ++m) _Pragma("unroll") for (int k = 0; k < 2; ++k) dst[m][k] = *(const PG8_LAS bf16x8*)(lds + PG8_SA(b, h) + aoff + m * 2048 + k * 1024); } while (0)
; #define PG8_LDB(dst, b, h) do { _Pragma("unroll") for (int n = 0; n < 2; ++n) _Pragma("unroll") for (int k = 0; k < 2; ++k) dst[n][k] = *(const PG8_LAS bf16x8*)(lds + PG8_SB(b, h) + boff + n * 2048 + k * 1024); } while (0)
; #define PG8_MMA(ai, bj, At, Bt) do { __builtin_amdgcn_s_setprio(1); _Pragma("unroll") for (int m = 0; m < 4; ++m) _Pragma("unroll") for (int n = 0; n < 2; ++n) _Pragma("unroll") for (int k = 0; k < 2; ++k) \
;         acc[ai][bj][m][n] = __builtin_amdgcn_mfma_f32_16x16x32_bf16(Bt[n][k], At[m][k], acc[ai][bj][m][n], 0, 0, 0); __builtin_amdgcn_s_setprio(0); } while (0)
; #define PG8_WAIT_V(n) asm volatile("s_waitcnt vmcnt(" #n ")" ::: "memory")
; #define PG8_WAIT_L(n) asm volatile("s_waitcnt lgkmcnt(" #n ")" ::: "memory")
; #define PG8_BAR __builtin_amdgcn_s_barrier()
; #define PG8_SCHED __builtin_amdgcn_sched_barrier(0)
; template <class Epi, class Sched, bool ALIGN_EPI = false, bool SP2 = false>
; __device__ __forceinline__ void gemm_phase(PG8_LAS unsigned char* lds, const Gemm g, const Sched& S, const Epi& E) {
;     ...
;             PG8_WAIT_V(8); PG8_WAIT_L(0); PG8_BAR; PG8_MMA(1, 0, At, B0); PG8_MMA(1, 1, At, B1); PG8_BAR; PG8_SCHED;
;             PG8_LDB(B0, 1, 0); PG8_LDB(B1, 1, 1); PG8_SCHED; PG8_LDA(At, 1, 0); PG8_STAGE(PG8_SA(0, 1), a2 + hstep, voffA);
;             PG8_WAIT_V(8); PG8_WAIT_L(0); PG8_BAR; PG8_MMA(0, 0, At, B0); PG8_MMA(0, 1, At, B1); PG8_BAR; PG8_SCHED;
	v_mfma_f32_16x16x32_bf16 v[32:35], v[180:183], v[196:199], v[32:35]
	v_mfma_f32_16x16x32_bf16 v[32:35], v[184:187], v[200:203], v[32:35]
	v_mfma_f32_16x16x32_bf16 v[48:51], v[180:183], v[188:191], v[48:51]
	v_mfma_f32_16x16x32_bf16 v[48:51], v[184:187], v[192:195], v[48:51]
	s_setprio 0
	s_add_i32 s62, 0, 0x18000
	v_add_u32_e32 v159, s62, v153
	s_add_i32 s63, 0, 0x1c000
	ds_read_b128 v[144:147], v159
	ds_read_b128 v[160:163], v159 offset:1024
	ds_read_b128 v[164:167], v159 offset:2048
	ds_read_b128 v[168:171], v159 offset:3072
	v_add_u32_e32 v159, s63, v153
	ds_read_b128 v[172:175], v159
	ds_read_b128 v[176:179], v159 offset:1024
	ds_read_b128 v[180:183], v159 offset:2048
	ds_read_b128 v[184:187], v159 offset:3072
	s_mov_b64 s[100:101], s[56:57]
	s_add_u32 s56, s56, 0x80000
	s_addc_u32 s57, s57, 0
	s_mov_b32 m0, s52
	ds_read_b128 v[188:191], v157 offset:32768
	ds_read_b128 v[192:195], v157 offset:33792
	ds_read_b128 v[196:199], v157 offset:34816
	ds_read_b128 v[200:203], v157 offset:35840
	ds_read_b128 v[204:207], v157 offset:36864
	ds_read_b128 v[208:211], v157 offset:37888
	ds_read_b128 v[212:215], v157 offset:38912
	ds_read_b128 v[216:219], v157 offset:39936
	global_load_lds_dwordx4 v128, s[56:57]
	s_mov_b32 m0, s53
	s_nop 0
	global_load_lds_dwordx4 v132, s[56:57]
	s_waitcnt vmcnt(8)
	s_waitcnt lgkmcnt(0)
	s_setprio 1
	s_barrier
	v_mfma_f32_16x16x32_bf16 v[124:127], v[144:147], v[188:191], v[124:127]
	v_mfma_f32_16x16x32_bf16 v[124:127], v[160:163], v[192:195], v[124:127]
	v_mfma_f32_16x16x32_bf16 v[108:111], v[144:147], v[196:199], v[108:111]
	v_mfma_f32_16x16x32_bf16 v[108:111], v[160:163], v[200:203], v[108:111]
	v_mfma_f32_16x16x32_bf16 v[92:95], v[144:147], v[204:207], v[92:95]
	v_mfma_f32_16x16x32_bf16 v[92:95], v[160:163], v[208:211], v[92:95]
	v_mfma_f32_16x16x32_bf16 v[76:79], v[144:147], v[212:215], v[76:79]
	v_mfma_f32_16x16x32_bf16 v[76:79], v[160:163], v[216:219], v[76:79]
	v_mfma_f32_16x16x32_bf16 v[72:75], v[164:167], v[212:215], v[72:75]
	v_mfma_f32_16x16x32_bf16 v[72:75], v[168:171], v[216:219], v[72:75]
	v_mfma_f32_16x16x32_bf16 v[88:91], v[164:167], v[204:207], v[88:91]
	v_mfma_f32_16x16x32_bf16 v[88:91], v[168:171], v[208:211], v[88:91]
	v_mfma_f32_16x16x32_bf16 v[104:107], v[164:167], v[196:199], v[104:107]
	v_mfma_f32_16x16x32_bf16 v[104:107], v[168:171], v[200:203], v[104:107]
	v_mfma_f32_16x16x32_bf16 v[120:123], v[164:167], v[188:191], v[120:123]
	v_mfma_f32_16x16x32_bf16 v[120:123], v[168:171], v[192:195], v[120:123]
	v_mfma_f32_16x16x32_bf16 v[116:119], v[172:175], v[188:191], v[116:119]
	v_mfma_f32_16x16x32_bf16 v[116:119], v[176:179], v[192:195], v[116:119]
	v_mfma_f32_16x16x32_bf16 v[100:103], v[172:175], v[196:199], v[100:103]
	v_mfma_f32_16x16x32_bf16 v[100:103], v[176:179], v[200:203], v[100:103]
	v_mfma_f32_16x16x32_bf16 v[84:87], v[172:175], v[204:207], v[84:87]
	v_mfma_f32_16x16x32_bf16 v[84:87], v[176:179], v[208:211], v[84:87]
	v_mfma_f32_16x16x32_bf16 v[68:71], v[172:175], v[212:215], v[68:71]
	v_mfma_f32_16x16x32_bf16 v[68:71], v[176:179], v[216:219], v[68:71]
	v_mfma_f32_16x16x32_bf16 v[64:67], v[180:183], v[212:215], v[64:67]
	v_mfma_f32_16x16x32_bf16 v[64:67], v[184:187], v[216:219], v[64:67]
	v_mfma_f32_16x16x32_bf16 v[80:83], v[180:183], v[204:207], v[80:83]
	v_mfma_f32_16x16x32_bf16 v[80:83], v[184:187], v[208:211], v[80:83]
	s_setprio 2
	s_barrier
; #define PG8_STAGE(bufoff, gbase, voff) do { _Pragma("unroll") for (int _i = 0; _i < 2; ++_i) \
;         __builtin_amdgcn_global_load_lds((const unsigned*)((const char*)(gbase) + (voff)[_i]), (PG8_LAS unsigned*)(lds + (bufoff) + ldsw + _i * 8192), 16, 0, 0); } while (0)
; #define PG8_LDA(dst, b, h) do { _Pragma("unroll") for (int m = 0; m < 4; ++m) _Pragma("unroll") for (int k = 0; k < 2; ++k) dst[m][k] = *(const PG8_LAS bf16x8*)(lds + PG8_SA(b, h) + aoff + m * 2048 + k * 1024); } while (0)
; #define PG8_MMA(ai, bj, At, Bt) do { __builtin_amdgcn_s_setprio(1); _Pragma("unroll") for (int m = 0; m < 4; ++m) _Pragma("unroll") for (int n = 0; n < 2; ++n) _Pragma("unroll") for (int k = 0; k < 2; ++k) \
;         acc[ai][bj][m][n] = __builtin_amdgcn_mfma_f32_16x16x32_bf16(Bt[n][k], At[m][k], acc[ai][bj][m][n], 0, 0, 0); __builtin_amdgcn_s_setprio(0); } while (0)
; #define PG8_WAIT_V(n) asm volatile("s_waitcnt vmcnt(" #n ")" ::: "memory")
; #define PG8_WAIT_L(n) asm volatile("s_waitcnt lgkmcnt(" #n ")" ::: "memory")
; #define PG8_BAR __builtin_amdgcn_s_barrier()
; #define PG8_SCHED __builtin_amdgcn_sched_barrier(0)
; template <class Epi, class Sched, bool ALIGN_EPI = false, bool SP2 = false>
; __device__ __forceinline__ void gemm_phase(PG8_LAS unsigned char* lds, const Gemm g, const Sched& S, const Epi& E) {
;     ...
;             PG8_WAIT_V(8); PG8_WAIT_L(0); PG8_BAR; PG8_MMA(0, 0, At, B0); PG8_MMA(0, 1, At, B1); PG8_BAR; PG8_SCHED;
;             PG8_LDA(At, 1, 1); PG8_STAGE(PG8_SB(1, 0), b3, voffB); PG8_STAGE(PG8_SB(1, 1), b3 + hstep, voffB); PG8_STAGE(PG8_SA(1, 0), a3, voffA);
;             PG8_WAIT_V(8); PG8_WAIT_L(0); PG8_BAR; PG8_MMA(1, 0, At, B0); PG8_MMA(1, 1, At, B1); PG8_BAR; PG8_SCHED;
;     ...
;         if constexpr (ALIGN_EPI) { if (wr == 0) PG8_BAR; }
	v_mfma_f32_16x16x32_bf16 v[96:99], v[180:183], v[196:199], v[96:99]
	v_mfma_f32_16x16x32_bf16 v[96:99], v[184:187], v[200:203], v[96:99]
	v_mfma_f32_16x16x32_bf16 v[112:115], v[180:183], v[188:191], v[112:115]
	v_mfma_f32_16x16x32_bf16 v[112:115], v[184:187], v[192:195], v[112:115]
	s_setprio 0
	s_add_i32 s56, s62, s3
	s_add_i32 m0, s56, 0xffffff80
	ds_read_b128 v[188:191], v157 offset:49152
	ds_read_b128 v[192:195], v157 offset:50176
	ds_read_b128 v[196:199], v157 offset:51200
	ds_read_b128 v[200:203], v157 offset:52224
	ds_read_b128 v[204:207], v157 offset:53248
	ds_read_b128 v[208:211], v157 offset:54272
	ds_read_b128 v[212:215], v157 offset:55296
	ds_read_b128 v[216:219], v157 offset:56320
	global_load_lds_dwordx4 v130, s[54:55] offset:128
	s_add_i32 m0, s56, 0x1f80
	s_mov_b64 s[98:99], s[54:55]
	s_add_u32 s54, s54, 0x80080
	s_addc_u32 s55, s55, 0
	s_add_i32 s56, s63, s3
	global_load_lds_dwordx4 v134, s[98:99] offset:128
	s_mov_b32 m0, s56
	s_nop 0
	global_load_lds_dwordx4 v130, s[54:55]
	s_add_i32 m0, s56, 0x2000
	s_nop 0
	global_load_lds_dwordx4 v134, s[54:55]
	s_add_i32 m0, s64, 0xffffff80
	s_nop 0
	global_load_lds_dwordx4 v128, s[100:101] offset:128
	s_add_i32 m0, s65, 0xffffff80
	s_nop 0
	global_load_lds_dwordx4 v132, s[100:101] offset:128
	s_waitcnt vmcnt(8)
	s_waitcnt lgkmcnt(0)
	s_setprio 1
	s_barrier
	v_mfma_f32_16x16x32_bf16 v[60:63], v[144:147], v[188:191], v[60:63]
	v_mfma_f32_16x16x32_bf16 v[60:63], v[160:163], v[192:195], v[60:63]
	v_mfma_f32_16x16x32_bf16 v[44:47], v[144:147], v[196:199], v[44:47]
	v_mfma_f32_16x16x32_bf16 v[44:47], v[160:163], v[200:203], v[44:47]
	v_mfma_f32_16x16x32_bf16 v[28:31], v[144:147], v[204:207], v[28:31]
	v_mfma_f32_16x16x32_bf16 v[28:31], v[160:163], v[208:211], v[28:31]
	v_mfma_f32_16x16x32_bf16 v[12:15], v[144:147], v[212:215], v[12:15]
	v_mfma_f32_16x16x32_bf16 v[12:15], v[160:163], v[216:219], v[12:15]
	v_mfma_f32_16x16x32_bf16 v[8:11], v[164:167], v[212:215], v[8:11]
	v_mfma_f32_16x16x32_bf16 v[8:11], v[168:171], v[216:219], v[8:11]
	v_mfma_f32_16x16x32_bf16 v[24:27], v[164:167], v[204:207], v[24:27]
	v_mfma_f32_16x16x32_bf16 v[24:27], v[168:171], v[208:211], v[24:27]
	v_mfma_f32_16x16x32_bf16 v[40:43], v[164:167], v[196:199], v[40:43]
	v_mfma_f32_16x16x32_bf16 v[40:43], v[168:171], v[200:203], v[40:43]
	v_mfma_f32_16x16x32_bf16 v[56:59], v[164:167], v[188:191], v[56:59]
	v_mfma_f32_16x16x32_bf16 v[56:59], v[168:171], v[192:195], v[56:59]
	v_mfma_f32_16x16x32_bf16 v[52:55], v[172:175], v[188:191], v[52:55]
	v_mfma_f32_16x16x32_bf16 v[52:55], v[176:179], v[192:195], v[52:55]
	v_mfma_f32_16x16x32_bf16 v[36:39], v[172:175], v[196:199], v[36:39]
	v_mfma_f32_16x16x32_bf16 v[36:39], v[176:179], v[200:203], v[36:39]
	v_mfma_f32_16x16x32_bf16 v[20:23], v[172:175], v[204:207], v[20:23]
	v_mfma_f32_16x16x32_bf16 v[20:23], v[176:179], v[208:211], v[20:23]
	v_mfma_f32_16x16x32_bf16 v[4:7], v[172:175], v[212:215], v[4:7]
	v_mfma_f32_16x16x32_bf16 v[4:7], v[176:179], v[216:219], v[4:7]
	v_mfma_f32_16x16x32_bf16 v[0:3], v[180:183], v[212:215], v[0:3]
	v_mfma_f32_16x16x32_bf16 v[0:3], v[184:187], v[216:219], v[0:3]
	v_mfma_f32_16x16x32_bf16 v[16:19], v[180:183], v[204:207], v[16:19]
	v_mfma_f32_16x16x32_bf16 v[16:19], v[184:187], v[208:211], v[16:19]
	s_setprio 2
	s_barrier
	v_mfma_f32_16x16x32_bf16 v[32:35], v[180:183], v[196:199], v[32:35]
	v_mfma_f32_16x16x32_bf16 v[32:35], v[184:187], v[200:203], v[32:35]
	v_mfma_f32_16x16x32_bf16 v[48:51], v[180:183], v[188:191], v[48:51]
	v_mfma_f32_16x16x32_bf16 v[48:51], v[184:187], v[192:195], v[48:51]
	s_setprio 0
	s_add_i32 s73, s73, 2
	s_add_u32 s50, s50, 0x100
	s_addc_u32 s51, s51, 0
	s_add_u32 s49, s49, 0x100
	s_addc_u32 s72, s72, 0
	s_cmp_gt_u32 s73, 29
	s_cbranch_scc0 .LBB0_557
	s_and_b64 vcc, exec, s[38:39]
	s_cbranch_vccz .LBB0_560
	s_barrier

; #define PG8_STAGE(bufoff, gbase, voff) do { _Pragma("unroll") for (int _i = 0; _i < 2; ++_i) \
;         __builtin_amdgcn_global_load_lds((const unsigned*)((const char*)(gbase) + (voff)[_i]), (PG8_LAS unsigned*)(lds + (bufoff) + ldsw + _i * 8192), 16, 0, 0); } while (0)
; #define PG8_LDA(dst, b, h) do { _Pragma("unroll") for (int m = 0; m < 4; ++m) _Pragma("unroll") for (int k = 0; k < 2; ++k) dst[m][k] = *(const PG8_LAS bf16x8*)(lds + PG8_SA(b, h) + aoff + m * 2048 + k * 1024); } while (0)
; #define PG8_LDB(dst, b, h) do { _Pragma("unroll") for (int n = 0; n < 2; ++n) _Pragma("unroll") for (int k = 0; k < 2; ++k) dst[n][k] = *(const PG8_LAS bf16x8*)(lds + PG8_SB(b, h) + boff + n * 2048 + k * 1024); } while (0)
; #define PG8_MMA(ai, bj, At, Bt) do { __builtin_amdgcn_s_setprio(1); _Pragma("unroll") for (int m = 0; m < 4; ++m) _Pragma("unroll") for (int n = 0; n < 2; ++n) _Pragma("unroll") for (int k = 0; k < 2; ++k) \
;         acc[ai][bj][m][n] = __builtin_amdgcn_mfma_f32_16x16x32_bf16(Bt[n][k], At[m][k], acc[ai][bj][m][n], 0, 0, 0); __builtin_amdgcn_s_setprio(0); } while (0)
; #define PG8_WAIT_V(n) asm volatile("s_waitcnt vmcnt(" #n ")" ::: "memory")
; #define PG8_WAIT_L(n) asm volatile("s_waitcnt lgkmcnt(" #n ")" ::: "memory")
; template <class Epi, class Sched, bool ALIGN_EPI = false, bool SP2 = false>
; __device__ __forceinline__ void gemm_phase(PG8_LAS unsigned char* lds, const Gemm g, const Sched& S, const Epi& E) {
;     ...
;             const bool last = (t == nt - 2);
;             const char* a1 = cA + (size_t)(t + 1) * kstep;
;             const char* a2 = last ? nA : cA + (size_t)(t + 2) * kstep; const char* b2 = last ? nB : cB + (size_t)(t + 2) * kstep;
;             const char* a3 = a2 + kstep; const char* b3 = b2 + kstep;
;             if (last && has_next) S.a_ready(nxt);
;             if constexpr (SP2) {
;             PG8_LDB(B0, 0, 0); PG8_LDB(B1, 0, 1); PG8_SCHED; PG8_LDA(At, 0, 0); PG8_STAGE(PG8_SA(1, 1), a1 + hstep, voffA);
;             PG8_WAIT_V(8); PG8_WAIT_L(0); PG8_BAR; PG8_MMA(0, 0, At, B0); PG8_MMA(0, 1, At, B1); PG8_BAR; PG8_SCHED;
;             PG8_LDA(At, 0, 1); PG8_STAGE(PG8_SB(0, 0), b2, voffB); PG8_STAGE(PG8_SB(0, 1), b2 + hstep, voffB); PG8_STAGE(PG8_SA(0, 0), a2, voffA);
;             PG8_WAIT_V(8); PG8_WAIT_L(0); PG8_BAR; PG8_MMA(1, 0, At, B0); PG8_MMA(1, 1, At, B1); PG8_BAR; PG8_SCHED;
.LBB0_700:
	ds_read_b128 v[164:167], v155
	ds_read_b128 v[168:171], v155 offset:1024
	ds_read_b128 v[172:175], v155 offset:2048
	ds_read_b128 v[176:179], v155 offset:3072
	ds_read_b128 v[180:183], v157
	ds_read_b128 v[184:187], v157 offset:1024
	ds_read_b128 v[188:191], v157 offset:2048
	ds_read_b128 v[192:195], v157 offset:3072
	s_add_u32 s46, s44, 0xfff80080
	s_addc_u32 s47, s45, -1
	s_cmp_eq_u32 s67, 28
	s_cselect_b32 s49, s10, s47
	s_cselect_b32 s48, s11, s46
	s_cselect_b32 s47, s21, s66
	s_cselect_b32 s46, s37, s65
	s_add_i32 m0, s43, 0xc000
	ds_read_b128 v[196:199], v159
	ds_read_b128 v[200:203], v159 offset:1024
	ds_read_b128 v[204:207], v159 offset:2048
	ds_read_b128 v[208:211], v159 offset:3072
	ds_read_b128 v[212:215], v159 offset:4096
	ds_read_b128 v[216:219], v159 offset:5120
	ds_read_b128 v[220:223], v159 offset:6144
	ds_read_b128 v[224:227], v159 offset:7168
	global_load_lds_dwordx4 v138, s[44:45]
	s_add_i32 m0, s43, 0xe000
	s_nop 0
	global_load_lds_dwordx4 v140, s[44:45]
	s_waitcnt vmcnt(8)
	s_waitcnt lgkmcnt(0)
	s_setprio 1
	s_barrier
	v_mfma_f32_16x16x32_bf16 v[124:127], v[164:167], v[196:199], v[124:127]
	v_mfma_f32_16x16x32_bf16 v[124:127], v[168:171], v[200:203], v[124:127]
	v_mfma_f32_16x16x32_bf16 v[108:111], v[164:167], v[204:207], v[108:111]
	v_mfma_f32_16x16x32_bf16 v[108:111], v[168:171], v[208:211], v[108:111]
	v_mfma_f32_16x16x32_bf16 v[92:95], v[164:167], v[212:215], v[92:95]
	v_mfma_f32_16x16x32_bf16 v[92:95], v[168:171], v[216:219], v[92:95]
	v_mfma_f32_16x16x32_bf16 v[76:79], v[164:167], v[220:223], v[76:79]
	v_mfma_f32_16x16x32_bf16 v[76:79], v[168:171], v[224:227], v[76:79]
	v_mfma_f32_16x16x32_bf16 v[72:75], v[172:175], v[220:223], v[72:75]
	v_mfma_f32_16x16x32_bf16 v[72:75], v[176:179], v[224:227], v[72:75]
	v_mfma_f32_16x16x32_bf16 v[88:91], v[172:175], v[212:215], v[88:91]
	v_mfma_f32_16x16x32_bf16 v[88:91], v[176:179], v[216:219], v[88:91]
	v_mfma_f32_16x16x32_bf16 v[104:107], v[172:175], v[204:207], v[104:107]
	v_mfma_f32_16x16x32_bf16 v[104:107], v[176:179], v[208:211], v[104:107]
	v_mfma_f32_16x16x32_bf16 v[120:123], v[172:175], v[196:199], v[120:123]
	v_mfma_f32_16x16x32_bf16 v[120:123], v[176:179], v[200:203], v[120:123]
	v_mfma_f32_16x16x32_bf16 v[116:119], v[180:183], v[196:199], v[116:119]
	v_mfma_f32_16x16x32_bf16 v[116:119], v[184:187], v[200:203], v[116:119]
	v_mfma_f32_16x16x32_bf16 v[100:103], v[180:183], v[204:207], v[100:103]
	v_mfma_f32_16x16x32_bf16 v[100:103], v[184:187], v[208:211], v[100:103]
	v_mfma_f32_16x16x32_bf16 v[84:87], v[180:183], v[212:215], v[84:87]
	v_mfma_f32_16x16x32_bf16 v[84:87], v[184:187], v[216:219], v[84:87]
	v_mfma_f32_16x16x32_bf16 v[68:71], v[180:183], v[220:223], v[68:71]
	v_mfma_f32_16x16x32_bf16 v[68:71], v[184:187], v[224:227], v[68:71]
	v_mfma_f32_16x16x32_bf16 v[64:67], v[188:191], v[220:223], v[64:67]
	v_mfma_f32_16x16x32_bf16 v[64:67], v[192:195], v[224:227], v[64:67]
	v_mfma_f32_16x16x32_bf16 v[80:83], v[188:191], v[212:215], v[80:83]
	v_mfma_f32_16x16x32_bf16 v[80:83], v[192:195], v[216:219], v[80:83]
	s_setprio 2
	s_barrier
	v_mfma_f32_16x16x32_bf16 v[96:99], v[188:191], v[204:207], v[96:99]
	v_mfma_f32_16x16x32_bf16 v[96:99], v[192:195], v[208:211], v[96:99]
	v_mfma_f32_16x16x32_bf16 v[112:115], v[188:191], v[196:199], v[112:115]
	v_mfma_f32_16x16x32_bf16 v[112:115], v[192:195], v[200:203], v[112:115]
	s_setprio 0
	s_add_i32 s62, s58, s3
	s_mov_b32 m0, s62
	ds_read_b128 v[196:199], v159 offset:16384
	ds_read_b128 v[200:203], v159 offset:17408
	ds_read_b128 v[204:207], v159 offset:18432
	ds_read_b128 v[208:211], v159 offset:19456
	ds_read_b128 v[212:215], v159 offset:20480
	ds_read_b128 v[216:219], v159 offset:21504
	ds_read_b128 v[220:223], v159 offset:22528
	ds_read_b128 v[224:227], v159 offset:23552
	global_load_lds_dwordx4 v130, s[46:47]
	s_add_i32 m0, s62, 0x2000
	s_add_u32 s62, s46, 0x80000
	s_addc_u32 s63, s47, 0
	s_add_i32 s68, s59, s3
	global_load_lds_dwordx4 v134, s[46:47]
	s_mov_b32 m0, s68
	s_nop 0
	global_load_lds_dwordx4 v130, s[62:63]
	s_add_i32 m0, s68, 0x2000
	s_nop 0
	global_load_lds_dwordx4 v134, s[62:63]
	s_mov_b32 m0, s43
	s_nop 0
	global_load_lds_dwordx4 v128, s[48:49]
	s_mov_b32 m0, s50
	s_nop 0
	global_load_lds_dwordx4 v132, s[48:49]
	s_waitcnt vmcnt(8)
	s_waitcnt lgkmcnt(0)
	s_setprio 1
	s_barrier
	v_mfma_f32_16x16x32_bf16 v[60:63], v[164:167], v[196:199], v[60:63]
	v_mfma_f32_16x16x32_bf16 v[60:63], v[168:171], v[200:203], v[60:63]
	v_mfma_f32_16x16x32_bf16 v[44:47], v[164:167], v[204:207], v[44:47]
	v_mfma_f32_16x16x32_bf16 v[44:47], v[168:171], v[208:211], v[44:47]
	v_mfma_f32_16x16x32_bf16 v[28:31], v[164:167], v[212:215], v[28:31]
	v_mfma_f32_16x16x32_bf16 v[28:31], v[168:171], v[216:219], v[28:31]
	v_mfma_f32_16x16x32_bf16 v[12:15], v[164:167], v[220:223], v[12:15]
	v_mfma_f32_16x16x32_bf16 v[12:15], v[168:171], v[224:227], v[12:15]
	v_mfma_f32_16x16x32_bf16 v[8:11], v[172:175], v[220:223], v[8:11]
	v_mfma_f32_16x16x32_bf16 v[8:11], v[176:179], v[224:227], v[8:11]
	v_mfma_f32_16x16x32_bf16 v[24:27], v[172:175], v[212:215], v[24:27]
	v_mfma_f32_16x16x32_bf16 v[24:27], v[176:179], v[216:219], v[24:27]
	v_mfma_f32_16x16x32_bf16 v[40:43], v[172:175], v[204:207], v[40:43]
	v_mfma_f32_16x16x32_bf16 v[40:43], v[176:179], v[208:211], v[40:43]
	v_mfma_f32_16x16x32_bf16 v[56:59], v[172:175], v[196:199], v[56:59]
	v_mfma_f32_16x16x32_bf16 v[56:59], v[176:179], v[200:203], v[56:59]
	v_mfma_f32_16x16x32_bf16 v[52:55], v[180:183], v[196:199], v[52:55]
	v_mfma_f32_16x16x32_bf16 v[52:55], v[184:187], v[200:203], v[52:55]
	v_mfma_f32_16x16x32_bf16 v[36:39], v[180:183], v[204:207], v[36:39]
	v_mfma_f32_16x16x32_bf16 v[36:39], v[184:187], v[208:211], v[36:39]
	v_mfma_f32_16x16x32_bf16 v[20:23], v[180:183], v[212:215], v[20:23]
	v_mfma_f32_16x16x32_bf16 v[20:23], v[184:187], v[216:219], v[20:23]
	v_mfma_f32_16x16x32_bf16 v[4:7], v[180:183], v[220:223], v[4:7]
	v_mfma_f32_16x16x32_bf16 v[4:7], v[184:187], v[224:227], v[4:7]
	v_mfma_f32_16x16x32_bf16 v[0:3], v[188:191], v[220:223], v[0:3]
	v_mfma_f32_16x16x32_bf16 v[0:3], v[192:195], v[224:227], v[0:3]
	v_mfma_f32_16x16x32_bf16 v[16:19], v[188:191], v[212:215], v[16:19]
	v_mfma_f32_16x16x32_bf16 v[16:19], v[192:195], v[216:219], v[16:19]
	s_setprio 2
	s_barrier
; #define PG8_STAGE(bufoff, gbase, voff) do { _Pragma("unroll") for (int _i = 0; _i < 2; ++_i) \
;         __builtin_amdgcn_global_load_lds((const unsigned*)((const char*)(gbase) + (voff)[_i]), (PG8_LAS unsigned*)(lds + (bufoff) + ldsw + _i * 8192), 16, 0, 0); } while (0)
; #define PG8_LDA(dst, b, h) do { _Pragma("unroll") for (int m = 0; m < 4; ++m) _Pragma("unroll") for (int k = 0; k < 2; ++k) dst[m][k] = *(const PG8_LAS bf16x8*)(lds + PG8_SA(b, h) + aoff + m * 2048 + k * 1024); } while (0)
; #define PG8_LDB(dst, b, h) do { _Pragma("unroll") for (int n = 0; n < 2; ++n) _Pragma("unroll") for (int k = 0; k < 2; ++k) dst[n][k] = *(const PG8_LAS bf16x8*)(lds + PG8_SB(b, h) + boff + n * 2048 + k * 1024); } while (0)
; #define PG8_MMA(ai, bj, At, Bt) do { __builtin_amdgcn_s_setprio(1); _Pragma("unroll") for (int m = 0; m < 4; ++m) _Pragma("unroll") for (int n = 0; n < 2; ++n) _Pragma("unroll") for (int k = 0; k < 2; ++k) \
;         acc[ai][bj][m][n] = __builtin_amdgcn_mfma_f32_16x16x32_bf16(Bt[n][k], At[m][k], acc[ai][bj][m][n], 0, 0, 0); __builtin_amdgcn_s_setprio(0); } while (0)
; #define PG8_WAIT_V(n) asm volatile("s_waitcnt vmcnt(" #n ")" ::: "memory")
; #define PG8_WAIT_L(n) asm volatile("s_waitcnt lgkmcnt(" #n ")" ::: "memory")
; #define PG8_BAR __builtin_amdgcn_s_barrier()
; #define PG8_SCHED __builtin_amdgcn_sched_barrier(0)
; template <class Epi, class Sched, bool ALIGN_EPI = false, bool SP2 = false>
; __device__ __forceinline__ void gemm_phase(PG8_LAS unsigned char* lds, const Gemm g, const Sched& S, const Epi& E) {
;     ...
;             PG8_WAIT_V(8); PG8_WAIT_L(0); PG8_BAR; PG8_MMA(1, 0, At, B0); PG8_MMA(1, 1, At, B1); PG8_BAR; PG8_SCHED;
;             PG8_LDB(B0, 1, 0); PG8_LDB(B1, 1, 1); PG8_SCHED; PG8_LDA(At, 1, 0); PG8_STAGE(PG8_SA(0, 1), a2 + hstep, voffA);
;             PG8_WAIT_V(8); PG8_WAIT_L(0); PG8_BAR; PG8_MMA(0, 0, At, B0); PG8_MMA(0, 1, At, B1); PG8_BAR; PG8_SCHED;
	v_mfma_f32_16x16x32_bf16 v[32:35], v[188:191], v[204:207], v[32:35]
	v_mfma_f32_16x16x32_bf16 v[32:35], v[192:195], v[208:211], v[32:35]
	v_mfma_f32_16x16x32_bf16 v[48:51], v[188:191], v[196:199], v[48:51]
	v_mfma_f32_16x16x32_bf16 v[48:51], v[192:195], v[200:203], v[48:51]
	s_setprio 0
	s_add_i32 s62, 0, 0x18000
	v_add_u32_e32 v161, s62, v147
	s_add_i32 s63, 0, 0x1c000
	ds_read_b128 v[164:167], v161
	ds_read_b128 v[168:171], v161 offset:1024
	ds_read_b128 v[172:175], v161 offset:2048
	ds_read_b128 v[176:179], v161 offset:3072
	v_add_u32_e32 v161, s63, v147
	ds_read_b128 v[180:183], v161
	ds_read_b128 v[184:187], v161 offset:1024
	ds_read_b128 v[188:191], v161 offset:2048
	ds_read_b128 v[192:195], v161 offset:3072
	s_mov_b64 s[100:101], s[48:49]
	s_add_u32 s48, s48, 0x80000
	s_addc_u32 s49, s49, 0
	s_mov_b32 m0, s51
	ds_read_b128 v[196:199], v159 offset:32768
	ds_read_b128 v[200:203], v159 offset:33792
	ds_read_b128 v[204:207], v159 offset:34816
	ds_read_b128 v[208:211], v159 offset:35840
	ds_read_b128 v[212:215], v159 offset:36864
	ds_read_b128 v[216:219], v159 offset:37888
	ds_read_b128 v[220:223], v159 offset:38912
	ds_read_b128 v[224:227], v159 offset:39936
	global_load_lds_dwordx4 v128, s[48:49]
	s_mov_b32 m0, s52
	s_nop 0
	global_load_lds_dwordx4 v132, s[48:49]
	s_waitcnt vmcnt(8)
	s_waitcnt lgkmcnt(0)
	s_setprio 1
	s_barrier
	v_mfma_f32_16x16x32_bf16 v[124:127], v[164:167], v[196:199], v[124:127]
	v_mfma_f32_16x16x32_bf16 v[124:127], v[168:171], v[200:203], v[124:127]
	v_mfma_f32_16x16x32_bf16 v[108:111], v[164:167], v[204:207], v[108:111]
	v_mfma_f32_16x16x32_bf16 v[108:111], v[168:171], v[208:211], v[108:111]
	v_mfma_f32_16x16x32_bf16 v[92:95], v[164:167], v[212:215], v[92:95]
	v_mfma_f32_16x16x32_bf16 v[92:95], v[168:171], v[216:219], v[92:95]
	v_mfma_f32_16x16x32_bf16 v[76:79], v[164:167], v[220:223], v[76:79]
	v_mfma_f32_16x16x32_bf16 v[76:79], v[168:171], v[224:227], v[76:79]
	v_mfma_f32_16x16x32_bf16 v[72:75], v[172:175], v[220:223], v[72:75]
	v_mfma_f32_16x16x32_bf16 v[72:75], v[176:179], v[224:227], v[72:75]
	v_mfma_f32_16x16x32_bf16 v[88:91], v[172:175], v[212:215], v[88:91]
	v_mfma_f32_16x16x32_bf16 v[88:91], v[176:179], v[216:219], v[88:91]
	v_mfma_f32_16x16x32_bf16 v[104:107], v[172:175], v[204:207], v[104:107]
	v_mfma_f32_16x16x32_bf16 v[104:107], v[176:179], v[208:211], v[104:107]
	v_mfma_f32_16x16x32_bf16 v[120:123], v[172:175], v[196:199], v[120:123]
	v_mfma_f32_16x16x32_bf16 v[120:123], v[176:179], v[200:203], v[120:123]
	v_mfma_f32_16x16x32_bf16 v[116:119], v[180:183], v[196:199], v[116:119]
	v_mfma_f32_16x16x32_bf16 v[116:119], v[184:187], v[200:203], v[116:119]
	v_mfma_f32_16x16x32_bf16 v[100:103], v[180:183], v[204:207], v[100:103]
	v_mfma_f32_16x16x32_bf16 v[100:103], v[184:187], v[208:211], v[100:103]
	v_mfma_f32_16x16x32_bf16 v[84:87], v[180:183], v[212:215], v[84:87]
	v_mfma_f32_16x16x32_bf16 v[84:87], v[184:187], v[216:219], v[84:87]
	v_mfma_f32_16x16x32_bf16 v[68:71], v[180:183], v[220:223], v[68:71]
	v_mfma_f32_16x16x32_bf16 v[68:71], v[184:187], v[224:227], v[68:71]
	v_mfma_f32_16x16x32_bf16 v[64:67], v[188:191], v[220:223], v[64:67]
	v_mfma_f32_16x16x32_bf16 v[64:67], v[192:195], v[224:227], v[64:67]
	v_mfma_f32_16x16x32_bf16 v[80:83], v[188:191], v[212:215], v[80:83]
	v_mfma_f32_16x16x32_bf16 v[80:83], v[192:195], v[216:219], v[80:83]
	s_setprio 2
	s_barrier
; #define PG8_STAGE(bufoff, gbase, voff) do { _Pragma("unroll") for (int _i = 0; _i < 2; ++_i) \
;         __builtin_amdgcn_global_load_lds((const unsigned*)((const char*)(gbase) + (voff)[_i]), (PG8_LAS unsigned*)(lds + (bufoff) + ldsw + _i * 8192), 16, 0, 0); } while (0)
; #define PG8_LDA(dst, b, h) do { _Pragma("unroll") for (int m = 0; m < 4; ++m) _Pragma("unroll") for (int k = 0; k < 2; ++k) dst[m][k] = *(const PG8_LAS bf16x8*)(lds + PG8_SA(b, h) + aoff + m * 2048 + k * 1024); } while (0)
; #define PG8_MMA(ai, bj, At, Bt) do { __builtin_amdgcn_s_setprio(1); _Pragma("unroll") for (int m = 0; m < 4; ++m) _Pragma("unroll") for (int n = 0; n < 2; ++n) _Pragma("unroll") for (int k = 0; k < 2; ++k) \
;         acc[ai][bj][m][n] = __builtin_amdgcn_mfma_f32_16x16x32_bf16(Bt[n][k], At[m][k], acc[ai][bj][m][n], 0, 0, 0); __builtin_amdgcn_s_setprio(0); } while (0)
; #define PG8_WAIT_V(n) asm volatile("s_waitcnt vmcnt(" #n ")" ::: "memory")
; #define PG8_WAIT_L(n) asm volatile("s_waitcnt lgkmcnt(" #n ")" ::: "memory")
; #define PG8_BAR __builtin_amdgcn_s_barrier()
; #define PG8_SCHED __builtin_amdgcn_sched_barrier(0)
; template <class Epi, class Sched, bool ALIGN_EPI = false, bool SP2 = false>
; __device__ __forceinline__ void gemm_phase(PG8_LAS unsigned char* lds, const Gemm g, const Sched& S, const Epi& E) {
;     ...
;             PG8_WAIT_V(8); PG8_WAIT_L(0); PG8_BAR; PG8_MMA(0, 0, At, B0); PG8_MMA(0, 1, At, B1); PG8_BAR; PG8_SCHED;
;             PG8_LDA(At, 1, 1); PG8_STAGE(PG8_SB(1, 0), b3, voffB); PG8_STAGE(PG8_SB(1, 1), b3 + hstep, voffB); PG8_STAGE(PG8_SA(1, 0), a3, voffA);
;             PG8_WAIT_V(8); PG8_WAIT_L(0); PG8_BAR; PG8_MMA(1, 0, At, B0); PG8_MMA(1, 1, At, B1); PG8_BAR; PG8_SCHED;
;     ...
;         if constexpr (ALIGN_EPI) { if (wr == 0) PG8_BAR; }
	v_mfma_f32_16x16x32_bf16 v[96:99], v[188:191], v[204:207], v[96:99]
	v_mfma_f32_16x16x32_bf16 v[96:99], v[192:195], v[208:211], v[96:99]
	v_mfma_f32_16x16x32_bf16 v[112:115], v[188:191], v[196:199], v[112:115]
	v_mfma_f32_16x16x32_bf16 v[112:115], v[192:195], v[200:203], v[112:115]
	s_setprio 0
	s_add_i32 s48, s62, s3
	s_add_i32 m0, s48, 0xffffff80
	ds_read_b128 v[196:199], v159 offset:49152
	ds_read_b128 v[200:203], v159 offset:50176
	ds_read_b128 v[204:207], v159 offset:51200
	ds_read_b128 v[208:211], v159 offset:52224
	ds_read_b128 v[212:215], v159 offset:53248
	ds_read_b128 v[216:219], v159 offset:54272
	ds_read_b128 v[220:223], v159 offset:55296
	ds_read_b128 v[224:227], v159 offset:56320
	global_load_lds_dwordx4 v130, s[46:47] offset:128
	s_add_i32 m0, s48, 0x1f80
	s_mov_b64 s[98:99], s[46:47]
	s_add_u32 s46, s46, 0x80080
	s_addc_u32 s47, s47, 0
	s_add_i32 s48, s63, s3
	global_load_lds_dwordx4 v134, s[98:99] offset:128
	s_mov_b32 m0, s48
	s_nop 0
	global_load_lds_dwordx4 v130, s[46:47]
	s_add_i32 m0, s48, 0x2000
	s_nop 0
	global_load_lds_dwordx4 v134, s[46:47]
	s_add_i32 m0, s55, 0xffffff80
	s_nop 0
	global_load_lds_dwordx4 v128, s[100:101] offset:128
	s_add_i32 m0, s56, 0xffffff80
	s_nop 0
	global_load_lds_dwordx4 v132, s[100:101] offset:128
	s_waitcnt vmcnt(8)
	s_waitcnt lgkmcnt(0)
	s_setprio 1
	s_barrier
	v_mfma_f32_16x16x32_bf16 v[60:63], v[164:167], v[196:199], v[60:63]
	v_mfma_f32_16x16x32_bf16 v[60:63], v[168:171], v[200:203], v[60:63]
	v_mfma_f32_16x16x32_bf16 v[44:47], v[164:167], v[204:207], v[44:47]
	v_mfma_f32_16x16x32_bf16 v[44:47], v[168:171], v[208:211], v[44:47]
	v_mfma_f32_16x16x32_bf16 v[28:31], v[164:167], v[212:215], v[28:31]
	v_mfma_f32_16x16x32_bf16 v[28:31], v[168:171], v[216:219], v[28:31]
	v_mfma_f32_16x16x32_bf16 v[12:15], v[164:167], v[220:223], v[12:15]
	v_mfma_f32_16x16x32_bf16 v[12:15], v[168:171], v[224:227], v[12:15]
	v_mfma_f32_16x16x32_bf16 v[8:11], v[172:175], v[220:223], v[8:11]
	v_mfma_f32_16x16x32_bf16 v[8:11], v[176:179], v[224:227], v[8:11]
	v_mfma_f32_16x16x32_bf16 v[24:27], v[172:175], v[212:215], v[24:27]
	v_mfma_f32_16x16x32_bf16 v[24:27], v[176:179], v[216:219], v[24:27]
	v_mfma_f32_16x16x32_bf16 v[40:43], v[172:175], v[204:207], v[40:43]
	v_mfma_f32_16x16x32_bf16 v[40:43], v[176:179], v[208:211], v[40:43]
	v_mfma_f32_16x16x32_bf16 v[56:59], v[172:175], v[196:199], v[56:59]
	v_mfma_f32_16x16x32_bf16 v[56:59], v[176:179], v[200:203], v[56:59]
	v_mfma_f32_16x16x32_bf16 v[52:55], v[180:183], v[196:199], v[52:55]
	v_mfma_f32_16x16x32_bf16 v[52:55], v[184:187], v[200:203], v[52:55]
	v_mfma_f32_16x16x32_bf16 v[36:39], v[180:183], v[204:207], v[36:39]
	v_mfma_f32_16x16x32_bf16 v[36:39], v[184:187], v[208:211], v[36:39]
	v_mfma_f32_16x16x32_bf16 v[20:23], v[180:183], v[212:215], v[20:23]
	v_mfma_f32_16x16x32_bf16 v[20:23], v[184:187], v[216:219], v[20:23]
	v_mfma_f32_16x16x32_bf16 v[4:7], v[180:183], v[220:223], v[4:7]
	v_mfma_f32_16x16x32_bf16 v[4:7], v[184:187], v[224:227], v[4:7]
	v_mfma_f32_16x16x32_bf16 v[0:3], v[188:191], v[220:223], v[0:3]
	v_mfma_f32_16x16x32_bf16 v[0:3], v[192:195], v[224:227], v[0:3]
	v_mfma_f32_16x16x32_bf16 v[16:19], v[188:191], v[212:215], v[16:19]
	v_mfma_f32_16x16x32_bf16 v[16:19], v[192:195], v[216:219], v[16:19]
	s_setprio 2
	s_barrier
	v_mfma_f32_16x16x32_bf16 v[32:35], v[188:191], v[204:207], v[32:35]
	v_mfma_f32_16x16x32_bf16 v[32:35], v[192:195], v[208:211], v[32:35]
	v_mfma_f32_16x16x32_bf16 v[48:51], v[188:191], v[196:199], v[48:51]
	v_mfma_f32_16x16x32_bf16 v[48:51], v[192:195], v[200:203], v[48:51]
	s_setprio 0
	s_add_i32 s67, s67, 2
	s_add_u32 s44, s44, 0x100
	s_addc_u32 s45, s45, 0
	s_add_u32 s65, s65, 0x100
	s_addc_u32 s66, s66, 0
	s_cmp_gt_u32 s67, 29
	s_cbranch_scc0 .LBB0_700
	s_and_b64 vcc, exec, s[12:13]
	s_cbranch_vccz .LBB0_703
	s_barrier

; #define PG8_STAGE(bufoff, gbase, voff) do { _Pragma("unroll") for (int _i = 0; _i < 2; ++_i) \
;         __builtin_amdgcn_global_load_lds((const unsigned*)((const char*)(gbase) + (voff)[_i]), (PG8_LAS unsigned*)(lds + (bufoff) + ldsw + _i * 8192), 16, 0, 0); } while (0)
; #define PG8_LDA(dst, b, h) do { _Pragma("unroll") for (int m = 0; m < 4; ++m) _Pragma("unroll") for (int k = 0; k < 2; ++k) dst[m][k] = *(const PG8_LAS bf16x8*)(lds + PG8_SA(b, h) + aoff + m * 2048 + k * 1024); } while (0)
; #define PG8_LDB(dst, b, h) do { _Pragma("unroll") for (int n = 0; n < 2; ++n) _Pragma("unroll") for (int k = 0; k < 2; ++k) dst[n][k] = *(const PG8_LAS bf16x8*)(lds + PG8_SB(b, h) + boff + n * 2048 + k * 1024); } while (0)
; #define PG8_MMA(ai, bj, At, Bt) do { __builtin_amdgcn_s_setprio(1); _Pragma("unroll") for (int m = 0; m < 4; ++m) _Pragma("unroll") for (int n = 0; n < 2; ++n) _Pragma("unroll") for (int k = 0; k < 2; ++k) \
;         acc[ai][bj][m][n] = __builtin_amdgcn_mfma_f32_16x16x32_bf16(Bt[n][k], At[m][k], acc[ai][bj][m][n], 0, 0, 0); __builtin_amdgcn_s_setprio(0); } while (0)
; #define PG8_WAIT_V(n) asm volatile("s_waitcnt vmcnt(" #n ")" ::: "memory")
; #define PG8_WAIT_L(n) asm volatile("s_waitcnt lgkmcnt(" #n ")" ::: "memory")
; template <class Epi, class Sched, bool ALIGN_EPI = false, bool SP2 = false>
; __device__ __forceinline__ void gemm_phase(PG8_LAS unsigned char* lds, const Gemm g, const Sched& S, const Epi& E) {
;     ...
;             const bool last = (t == nt - 2);
;             const char* a1 = cA + (size_t)(t + 1) * kstep;
;             const char* a2 = last ? nA : cA + (size_t)(t + 2) * kstep; const char* b2 = last ? nB : cB + (size_t)(t + 2) * kstep;
;             const char* a3 = a2 + kstep; const char* b3 = b2 + kstep;
;             if (last && has_next) S.a_ready(nxt);
;             if constexpr (SP2) {
;             PG8_LDB(B0, 0, 0); PG8_LDB(B1, 0, 1); PG8_SCHED; PG8_LDA(At, 0, 0); PG8_STAGE(PG8_SA(1, 1), a1 + hstep, voffA);
;             PG8_WAIT_V(8); PG8_WAIT_L(0); PG8_BAR; PG8_MMA(0, 0, At, B0); PG8_MMA(0, 1, At, B1); PG8_BAR; PG8_SCHED;
;             PG8_LDA(At, 0, 1); PG8_STAGE(PG8_SB(0, 0), b2, voffB); PG8_STAGE(PG8_SB(0, 1), b2 + hstep, voffB); PG8_STAGE(PG8_SA(0, 0), a2, voffA);
;             PG8_WAIT_V(8); PG8_WAIT_L(0); PG8_BAR; PG8_MMA(1, 0, At, B0); PG8_MMA(1, 1, At, B1); PG8_BAR; PG8_SCHED;
.LBB0_779:
	ds_read_b128 v[144:147], v155
	ds_read_b128 v[160:163], v155 offset:1024
	ds_read_b128 v[164:167], v155 offset:2048
	ds_read_b128 v[168:171], v155 offset:3072
	ds_read_b128 v[172:175], v156
	ds_read_b128 v[176:179], v156 offset:1024
	ds_read_b128 v[180:183], v156 offset:2048
	ds_read_b128 v[184:187], v156 offset:3072
	s_add_u32 s40, s38, 0xffea0080
	s_addc_u32 s41, s39, -1
	s_cmpk_eq_i32 s58, 0x54
	s_cselect_b32 s43, s7, s41
	s_cselect_b32 s42, s6, s40
	s_cselect_b32 s41, s37, s57
	s_cselect_b32 s40, s36, s11
	s_add_i32 m0, s33, 0xc000
	ds_read_b128 v[188:191], v157
	ds_read_b128 v[192:195], v157 offset:1024
	ds_read_b128 v[196:199], v157 offset:2048
	ds_read_b128 v[200:203], v157 offset:3072
	ds_read_b128 v[204:207], v157 offset:4096
	ds_read_b128 v[208:211], v157 offset:5120
	ds_read_b128 v[212:215], v157 offset:6144
	ds_read_b128 v[216:219], v157 offset:7168
	global_load_lds_dwordx4 v136, s[38:39]
	s_add_i32 m0, s33, 0xe000
	s_nop 0
	global_load_lds_dwordx4 v138, s[38:39]
	s_waitcnt vmcnt(8)
	s_waitcnt lgkmcnt(0)
	s_setprio 1
	s_barrier
	v_mfma_f32_16x16x32_bf16 v[124:127], v[144:147], v[188:191], v[124:127]
	v_mfma_f32_16x16x32_bf16 v[124:127], v[160:163], v[192:195], v[124:127]
	v_mfma_f32_16x16x32_bf16 v[108:111], v[144:147], v[196:199], v[108:111]
	v_mfma_f32_16x16x32_bf16 v[108:111], v[160:163], v[200:203], v[108:111]
	v_mfma_f32_16x16x32_bf16 v[92:95], v[144:147], v[204:207], v[92:95]
	v_mfma_f32_16x16x32_bf16 v[92:95], v[160:163], v[208:211], v[92:95]
	v_mfma_f32_16x16x32_bf16 v[76:79], v[144:147], v[212:215], v[76:79]
	v_mfma_f32_16x16x32_bf16 v[76:79], v[160:163], v[216:219], v[76:79]
	v_mfma_f32_16x16x32_bf16 v[72:75], v[164:167], v[212:215], v[72:75]
	v_mfma_f32_16x16x32_bf16 v[72:75], v[168:171], v[216:219], v[72:75]
	v_mfma_f32_16x16x32_bf16 v[88:91], v[164:167], v[204:207], v[88:91]
	v_mfma_f32_16x16x32_bf16 v[88:91], v[168:171], v[208:211], v[88:91]
	v_mfma_f32_16x16x32_bf16 v[104:107], v[164:167], v[196:199], v[104:107]
	v_mfma_f32_16x16x32_bf16 v[104:107], v[168:171], v[200:203], v[104:107]
	v_mfma_f32_16x16x32_bf16 v[120:123], v[164:167], v[188:191], v[120:123]
	v_mfma_f32_16x16x32_bf16 v[120:123], v[168:171], v[192:195], v[120:123]
	v_mfma_f32_16x16x32_bf16 v[116:119], v[172:175], v[188:191], v[116:119]
	v_mfma_f32_16x16x32_bf16 v[116:119], v[176:179], v[192:195], v[116:119]
	v_mfma_f32_16x16x32_bf16 v[100:103], v[172:175], v[196:199], v[100:103]
	v_mfma_f32_16x16x32_bf16 v[100:103], v[176:179], v[200:203], v[100:103]
	v_mfma_f32_16x16x32_bf16 v[84:87], v[172:175], v[204:207], v[84:87]
	v_mfma_f32_16x16x32_bf16 v[84:87], v[176:179], v[208:211], v[84:87]
	v_mfma_f32_16x16x32_bf16 v[68:71], v[172:175], v[212:215], v[68:71]
	v_mfma_f32_16x16x32_bf16 v[68:71], v[176:179], v[216:219], v[68:71]
	v_mfma_f32_16x16x32_bf16 v[64:67], v[180:183], v[212:215], v[64:67]
	v_mfma_f32_16x16x32_bf16 v[64:67], v[184:187], v[216:219], v[64:67]
	v_mfma_f32_16x16x32_bf16 v[80:83], v[180:183], v[204:207], v[80:83]
	v_mfma_f32_16x16x32_bf16 v[80:83], v[184:187], v[208:211], v[80:83]
	s_setprio 2
	s_barrier
	v_mfma_f32_16x16x32_bf16 v[96:99], v[180:183], v[196:199], v[96:99]
	v_mfma_f32_16x16x32_bf16 v[96:99], v[184:187], v[200:203], v[96:99]
	v_mfma_f32_16x16x32_bf16 v[112:115], v[180:183], v[188:191], v[112:115]
	v_mfma_f32_16x16x32_bf16 v[112:115], v[184:187], v[192:195], v[112:115]
	s_setprio 0
	s_add_i32 s59, s52, s3
	s_mov_b32 m0, s59
	ds_read_b128 v[188:191], v157 offset:16384
	ds_read_b128 v[192:195], v157 offset:17408
	ds_read_b128 v[196:199], v157 offset:18432
	ds_read_b128 v[200:203], v157 offset:19456
	ds_read_b128 v[204:207], v157 offset:20480
	ds_read_b128 v[208:211], v157 offset:21504
	ds_read_b128 v[212:215], v157 offset:22528
	ds_read_b128 v[216:219], v157 offset:23552
	global_load_lds_dwordx4 v130, s[40:41]
	s_add_i32 m0, s59, 0x2000
	s_add_u32 s62, s40, 0x160000
	s_addc_u32 s63, s41, 0
	s_add_i32 s59, s53, s3
	global_load_lds_dwordx4 v134, s[40:41]
	s_mov_b32 m0, s59
	s_nop 0
	global_load_lds_dwordx4 v130, s[62:63]
	s_add_i32 m0, s59, 0x2000
	s_nop 0
	global_load_lds_dwordx4 v134, s[62:63]
	s_mov_b32 m0, s33
	s_nop 0
	global_load_lds_dwordx4 v128, s[42:43]
	s_mov_b32 m0, s35
	s_nop 0
	global_load_lds_dwordx4 v132, s[42:43]
	s_waitcnt vmcnt(8)
	s_waitcnt lgkmcnt(0)
	s_setprio 1
	s_barrier
	v_mfma_f32_16x16x32_bf16 v[60:63], v[144:147], v[188:191], v[60:63]
	v_mfma_f32_16x16x32_bf16 v[60:63], v[160:163], v[192:195], v[60:63]
	v_mfma_f32_16x16x32_bf16 v[44:47], v[144:147], v[196:199], v[44:47]
	v_mfma_f32_16x16x32_bf16 v[44:47], v[160:163], v[200:203], v[44:47]
	v_mfma_f32_16x16x32_bf16 v[28:31], v[144:147], v[204:207], v[28:31]
	v_mfma_f32_16x16x32_bf16 v[28:31], v[160:163], v[208:211], v[28:31]
	v_mfma_f32_16x16x32_bf16 v[12:15], v[144:147], v[212:215], v[12:15]
	v_mfma_f32_16x16x32_bf16 v[12:15], v[160:163], v[216:219], v[12:15]
	v_mfma_f32_16x16x32_bf16 v[8:11], v[164:167], v[212:215], v[8:11]
	v_mfma_f32_16x16x32_bf16 v[8:11], v[168:171], v[216:219], v[8:11]
	v_mfma_f32_16x16x32_bf16 v[24:27], v[164:167], v[204:207], v[24:27]
	v_mfma_f32_16x16x32_bf16 v[24:27], v[168:171], v[208:211], v[24:27]
	v_mfma_f32_16x16x32_bf16 v[40:43], v[164:167], v[196:199], v[40:43]
	v_mfma_f32_16x16x32_bf16 v[40:43], v[168:171], v[200:203], v[40:43]
	v_mfma_f32_16x16x32_bf16 v[56:59], v[164:167], v[188:191], v[56:59]
	v_mfma_f32_16x16x32_bf16 v[56:59], v[168:171], v[192:195], v[56:59]
	v_mfma_f32_16x16x32_bf16 v[52:55], v[172:175], v[188:191], v[52:55]
	v_mfma_f32_16x16x32_bf16 v[52:55], v[176:179], v[192:195], v[52:55]
	v_mfma_f32_16x16x32_bf16 v[36:39], v[172:175], v[196:199], v[36:39]
	v_mfma_f32_16x16x32_bf16 v[36:39], v[176:179], v[200:203], v[36:39]
	v_mfma_f32_16x16x32_bf16 v[20:23], v[172:175], v[204:207], v[20:23]
	v_mfma_f32_16x16x32_bf16 v[20:23], v[176:179], v[208:211], v[20:23]
	v_mfma_f32_16x16x32_bf16 v[4:7], v[172:175], v[212:215], v[4:7]
	v_mfma_f32_16x16x32_bf16 v[4:7], v[176:179], v[216:219], v[4:7]
	v_mfma_f32_16x16x32_bf16 v[0:3], v[180:183], v[212:215], v[0:3]
	v_mfma_f32_16x16x32_bf16 v[0:3], v[184:187], v[216:219], v[0:3]
	v_mfma_f32_16x16x32_bf16 v[16:19], v[180:183], v[204:207], v[16:19]
	v_mfma_f32_16x16x32_bf16 v[16:19], v[184:187], v[208:211], v[16:19]
	s_setprio 2
	s_barrier
; #define PG8_STAGE(bufoff, gbase, voff) do { _Pragma("unroll") for (int _i = 0; _i < 2; ++_i) \
;         __builtin_amdgcn_global_load_lds((const unsigned*)((const char*)(gbase) + (voff)[_i]), (PG8_LAS unsigned*)(lds + (bufoff) + ldsw + _i * 8192), 16, 0, 0); } while (0)
; #define PG8_LDA(dst, b, h) do { _Pragma("unroll") for (int m = 0; m < 4; ++m) _Pragma("unroll") for (int k = 0; k < 2; ++k) dst[m][k] = *(const PG8_LAS bf16x8*)(lds + PG8_SA(b, h) + aoff + m * 2048 + k * 1024); } while (0)
; #define PG8_LDB(dst, b, h) do { _Pragma("unroll") for (int n = 0; n < 2; ++n) _Pragma("unroll") for (int k = 0; k < 2; ++k) dst[n][k] = *(const PG8_LAS bf16x8*)(lds + PG8_SB(b, h) + boff + n * 2048 + k * 1024); } while (0)
; #define PG8_SCHED __builtin_amdgcn_sched_barrier(0)
; template <class Epi, class Sched, bool ALIGN_EPI = false, bool SP2 = false>
; __device__ __forceinline__ void gemm_phase(PG8_LAS unsigned char* lds, const Gemm g, const Sched& S, const Epi& E) {
;     ...
;             PG8_LDB(B0, 1, 0); PG8_LDB(B1, 1, 1); PG8_SCHED; PG8_LDA(At, 1, 0); PG8_STAGE(PG8_SA(0, 1), a2 + hstep, voffA);
	v_mfma_f32_16x16x32_bf16 v[32:35], v[180:183], v[196:199], v[32:35]
	v_mfma_f32_16x16x32_bf16 v[32:35], v[184:187], v[200:203], v[32:35]
	v_mfma_f32_16x16x32_bf16 v[48:51], v[180:183], v[188:191], v[48:51]
	v_mfma_f32_16x16x32_bf16 v[48:51], v[184:187], v[192:195], v[48:51]
	s_setprio 0
	s_add_i32 s59, 0, 0x18000
	v_add_u32_e32 v159, s59, v153
	s_add_i32 s61, 0, 0x1c000
	ds_read_b128 v[144:147], v159
	ds_read_b128 v[160:163], v159 offset:1024
	ds_read_b128 v[164:167], v159 offset:2048
	ds_read_b128 v[168:171], v159 offset:3072
	v_add_u32_e32 v159, s61, v153
	ds_read_b128 v[172:175], v159
	ds_read_b128 v[176:179], v159 offset:1024
	ds_read_b128 v[180:183], v159 offset:2048
	ds_read_b128 v[184:187], v159 offset:3072
	s_mov_b64 s[100:101], s[42:43]
	s_add_u32 s42, s42, 0x160000
	s_addc_u32 s43, s43, 0
	s_mov_b32 m0, s44
	ds_read_b128 v[188:191], v157 offset:32768
	ds_read_b128 v[192:195], v157 offset:33792
	ds_read_b128 v[196:199], v157 offset:34816
	ds_read_b128 v[200:203], v157 offset:35840
	ds_read_b128 v[204:207], v157 offset:36864
	ds_read_b128 v[208:211], v157 offset:37888
	ds_read_b128 v[212:215], v157 offset:38912
	ds_read_b128 v[216:219], v157 offset:39936
	global_load_lds_dwordx4 v128, s[42:43]
	s_mov_b32 m0, s45
	s_nop 0
	global_load_lds_dwordx4 v132, s[42:43]
	s_waitcnt vmcnt(8)
	s_waitcnt lgkmcnt(0)
	s_setprio 1
	s_barrier
	v_mfma_f32_16x16x32_bf16 v[124:127], v[144:147], v[188:191], v[124:127]
	v_mfma_f32_16x16x32_bf16 v[124:127], v[160:163], v[192:195], v[124:127]
	v_mfma_f32_16x16x32_bf16 v[108:111], v[144:147], v[196:199], v[108:111]
	v_mfma_f32_16x16x32_bf16 v[108:111], v[160:163], v[200:203], v[108:111]
	v_mfma_f32_16x16x32_bf16 v[92:95], v[144:147], v[204:207], v[92:95]
	v_mfma_f32_16x16x32_bf16 v[92:95], v[160:163], v[208:211], v[92:95]
	v_mfma_f32_16x16x32_bf16 v[76:79], v[144:147], v[212:215], v[76:79]
	v_mfma_f32_16x16x32_bf16 v[76:79], v[160:163], v[216:219], v[76:79]
	v_mfma_f32_16x16x32_bf16 v[72:75], v[164:167], v[212:215], v[72:75]
	v_mfma_f32_16x16x32_bf16 v[72:75], v[168:171], v[216:219], v[72:75]
	v_mfma_f32_16x16x32_bf16 v[88:91], v[164:167], v[204:207], v[88:91]
	v_mfma_f32_16x16x32_bf16 v[88:91], v[168:171], v[208:211], v[88:91]
	v_mfma_f32_16x16x32_bf16 v[104:107], v[164:167], v[196:199], v[104:107]
	v_mfma_f32_16x16x32_bf16 v[104:107], v[168:171], v[200:203], v[104:107]
	v_mfma_f32_16x16x32_bf16 v[120:123], v[164:167], v[188:191], v[120:123]
	v_mfma_f32_16x16x32_bf16 v[120:123], v[168:171], v[192:195], v[120:123]
	v_mfma_f32_16x16x32_bf16 v[116:119], v[172:175], v[188:191], v[116:119]
	v_mfma_f32_16x16x32_bf16 v[116:119], v[176:179], v[192:195], v[116:119]
	v_mfma_f32_16x16x32_bf16 v[100:103], v[172:175], v[196:199], v[100:103]
	v_mfma_f32_16x16x32_bf16 v[100:103], v[176:179], v[200:203], v[100:103]
	v_mfma_f32_16x16x32_bf16 v[84:87], v[172:175], v[204:207], v[84:87]
	v_mfma_f32_16x16x32_bf16 v[84:87], v[176:179], v[208:211], v[84:87]
	v_mfma_f32_16x16x32_bf16 v[68:71], v[172:175], v[212:215], v[68:71]
	v_mfma_f32_16x16x32_bf16 v[68:71], v[176:179], v[216:219], v[68:71]
	v_mfma_f32_16x16x32_bf16 v[64:67], v[180:183], v[212:215], v[64:67]
	v_mfma_f32_16x16x32_bf16 v[64:67], v[184:187], v[216:219], v[64:67]
	v_mfma_f32_16x16x32_bf16 v[80:83], v[180:183], v[204:207], v[80:83]
	v_mfma_f32_16x16x32_bf16 v[80:83], v[184:187], v[208:211], v[80:83]
	s_setprio 2
	s_barrier
; #define PG8_STAGE(bufoff, gbase, voff) do { _Pragma("unroll") for (int _i = 0; _i < 2; ++_i) \
;         __builtin_amdgcn_global_load_lds((const unsigned*)((const char*)(gbase) + (voff)[_i]), (PG8_LAS unsigned*)(lds + (bufoff) + ldsw + _i * 8192), 16, 0, 0); } while (0)
; #define PG8_LDA(dst, b, h) do { _Pragma("unroll") for (int m = 0; m < 4; ++m) _Pragma("unroll") for (int k = 0; k < 2; ++k) dst[m][k] = *(const PG8_LAS bf16x8*)(lds + PG8_SA(b, h) + aoff + m * 2048 + k * 1024); } while (0)
; #define PG8_MMA(ai, bj, At, Bt) do { __builtin_amdgcn_s_setprio(1); _Pragma("unroll") for (int m = 0; m < 4; ++m) _Pragma("unroll") for (int n = 0; n < 2; ++n) _Pragma("unroll") for (int k = 0; k < 2; ++k) \
;         acc[ai][bj][m][n] = __builtin_amdgcn_mfma_f32_16x16x32_bf16(Bt[n][k], At[m][k], acc[ai][bj][m][n], 0, 0, 0); __builtin_amdgcn_s_setprio(0); } while (0)
; #define PG8_WAIT_V(n) asm volatile("s_waitcnt vmcnt(" #n ")" ::: "memory")
; #define PG8_WAIT_L(n) asm volatile("s_waitcnt lgkmcnt(" #n ")" ::: "memory")
; #define PG8_BAR __builtin_amdgcn_s_barrier()
; #define PG8_SCHED __builtin_amdgcn_sched_barrier(0)
; template <class Epi, class Sched, bool ALIGN_EPI = false, bool SP2 = false>
; __device__ __forceinline__ void gemm_phase(PG8_LAS unsigned char* lds, const Gemm g, const Sched& S, const Epi& E) {
;     ...
;         for (int t = 0; t < nt; t += 2) {
;     ...
;             PG8_LDA(At, 1, 1); PG8_STAGE(PG8_SB(1, 0), b3, voffB); PG8_STAGE(PG8_SB(1, 1), b3 + hstep, voffB); PG8_STAGE(PG8_SA(1, 0), a3, voffA);
;             PG8_WAIT_V(8); PG8_WAIT_L(0); PG8_BAR; PG8_MMA(1, 0, At, B0); PG8_MMA(1, 1, At, B1); PG8_BAR; PG8_SCHED;
	v_mfma_f32_16x16x32_bf16 v[96:99], v[180:183], v[196:199], v[96:99]
	v_mfma_f32_16x16x32_bf16 v[96:99], v[184:187], v[200:203], v[96:99]
	v_mfma_f32_16x16x32_bf16 v[112:115], v[180:183], v[188:191], v[112:115]
	v_mfma_f32_16x16x32_bf16 v[112:115], v[184:187], v[192:195], v[112:115]
	s_setprio 0
	s_add_i32 s42, s59, s3
	s_add_i32 m0, s42, 0xffffff80
	ds_read_b128 v[188:191], v157 offset:49152
	ds_read_b128 v[192:195], v157 offset:50176
	ds_read_b128 v[196:199], v157 offset:51200
	ds_read_b128 v[200:203], v157 offset:52224
	ds_read_b128 v[204:207], v157 offset:53248
	ds_read_b128 v[208:211], v157 offset:54272
	ds_read_b128 v[212:215], v157 offset:55296
	ds_read_b128 v[216:219], v157 offset:56320
	global_load_lds_dwordx4 v130, s[40:41] offset:128
	s_add_i32 m0, s42, 0x1f80
	s_mov_b64 s[98:99], s[40:41]
	s_add_u32 s40, s40, 0x160080
	s_addc_u32 s41, s41, 0
	s_add_i32 s42, s61, s3
	global_load_lds_dwordx4 v134, s[98:99] offset:128
	s_mov_b32 m0, s42
	s_nop 0
	global_load_lds_dwordx4 v130, s[40:41]
	s_add_i32 m0, s42, 0x2000
	s_nop 0
	global_load_lds_dwordx4 v134, s[40:41]
	s_add_i32 m0, s49, 0xffffff80
	s_nop 0
	global_load_lds_dwordx4 v128, s[100:101] offset:128
	s_add_i32 m0, s50, 0xffffff80
	s_nop 0
	global_load_lds_dwordx4 v132, s[100:101] offset:128
	s_waitcnt vmcnt(8)
	s_waitcnt lgkmcnt(0)
	s_setprio 1
	s_barrier
	v_mfma_f32_16x16x32_bf16 v[60:63], v[144:147], v[188:191], v[60:63]
	v_mfma_f32_16x16x32_bf16 v[60:63], v[160:163], v[192:195], v[60:63]
	v_mfma_f32_16x16x32_bf16 v[44:47], v[144:147], v[196:199], v[44:47]
	v_mfma_f32_16x16x32_bf16 v[44:47], v[160:163], v[200:203], v[44:47]
	v_mfma_f32_16x16x32_bf16 v[28:31], v[144:147], v[204:207], v[28:31]
	v_mfma_f32_16x16x32_bf16 v[28:31], v[160:163], v[208:211], v[28:31]
	v_mfma_f32_16x16x32_bf16 v[12:15], v[144:147], v[212:215], v[12:15]
	v_mfma_f32_16x16x32_bf16 v[12:15], v[160:163], v[216:219], v[12:15]
	v_mfma_f32_16x16x32_bf16 v[8:11], v[164:167], v[212:215], v[8:11]
	v_mfma_f32_16x16x32_bf16 v[8:11], v[168:171], v[216:219], v[8:11]
	v_mfma_f32_16x16x32_bf16 v[24:27], v[164:167], v[204:207], v[24:27]
	v_mfma_f32_16x16x32_bf16 v[24:27], v[168:171], v[208:211], v[24:27]
	v_mfma_f32_16x16x32_bf16 v[40:43], v[164:167], v[196:199], v[40:43]
	v_mfma_f32_16x16x32_bf16 v[40:43], v[168:171], v[200:203], v[40:43]
	v_mfma_f32_16x16x32_bf16 v[56:59], v[164:167], v[188:191], v[56:59]
	v_mfma_f32_16x16x32_bf16 v[56:59], v[168:171], v[192:195], v[56:59]
	v_mfma_f32_16x16x32_bf16 v[52:55], v[172:175], v[188:191], v[52:55]
	v_mfma_f32_16x16x32_bf16 v[52:55], v[176:179], v[192:195], v[52:55]
	v_mfma_f32_16x16x32_bf16 v[36:39], v[172:175], v[196:199], v[36:39]
	v_mfma_f32_16x16x32_bf16 v[36:39], v[176:179], v[200:203], v[36:39]
	v_mfma_f32_16x16x32_bf16 v[20:23], v[172:175], v[204:207], v[20:23]
	v_mfma_f32_16x16x32_bf16 v[20:23], v[176:179], v[208:211], v[20:23]
	v_mfma_f32_16x16x32_bf16 v[4:7], v[172:175], v[212:215], v[4:7]
	v_mfma_f32_16x16x32_bf16 v[4:7], v[176:179], v[216:219], v[4:7]
	v_mfma_f32_16x16x32_bf16 v[0:3], v[180:183], v[212:215], v[0:3]
	v_mfma_f32_16x16x32_bf16 v[0:3], v[184:187], v[216:219], v[0:3]
	v_mfma_f32_16x16x32_bf16 v[16:19], v[180:183], v[204:207], v[16:19]
	v_mfma_f32_16x16x32_bf16 v[16:19], v[184:187], v[208:211], v[16:19]
	s_setprio 2
	s_barrier
	v_mfma_f32_16x16x32_bf16 v[32:35], v[180:183], v[196:199], v[32:35]
	v_mfma_f32_16x16x32_bf16 v[32:35], v[184:187], v[200:203], v[32:35]
	v_mfma_f32_16x16x32_bf16 v[48:51], v[180:183], v[188:191], v[48:51]
	v_mfma_f32_16x16x32_bf16 v[48:51], v[184:187], v[192:195], v[48:51]
	s_setprio 0
	s_add_i32 s58, s58, 2
	s_add_u32 s38, s38, 0x100
	s_addc_u32 s39, s39, 0
	s_add_u32 s11, s11, 0x100
	s_addc_u32 s57, s57, 0
	s_cmpk_gt_u32 s58, 0x55
	s_cbranch_scc0 .LBB0_779
	s_and_b64 vcc, exec, s[20:21]
	s_cbranch_vccz .LBB0_782
	s_barrier
